# removed the per-phase s_setprio 1/0 toggles inside the five live GEMM K-loops
# speedup vs baseline: 1.0139x; 1.0075x over previous
.LBB0_267:
	s_add_u32 s12, s4, 0xfffc0080
	s_addc_u32 s13, s5, -1
	s_add_i32 s86, 0, 0x10000
	v_add_u32_e32 v0, s86, v150
	ds_read_b128 v[142:145], v0
	ds_read_b128 v[146:149], v0 offset:1024
	ds_read_b128 v[152:155], v0 offset:2048
	ds_read_b128 v[156:159], v0 offset:3072
	s_cmp_eq_u32 s85, 12
	s_cselect_b32 s15, s44, s13
	s_cselect_b32 s14, s45, s12
	s_cselect_b32 s13, s47, s79
	s_cselect_b32 s12, s55, s78
	v_lshl_add_u64 v[194:195], s[4:5], 0, v[138:139]
	s_add_i32 m0, s7, 0xc000
	ds_read_b128 v[160:163], v151
	ds_read_b128 v[164:167], v151 offset:1024
	ds_read_b128 v[168:171], v151 offset:2048
	ds_read_b128 v[172:175], v151 offset:3072
	ds_read_b128 v[176:179], v151 offset:4096
	ds_read_b128 v[180:183], v151 offset:5120
	ds_read_b128 v[184:187], v151 offset:6144
	ds_read_b128 v[190:193], v151 offset:7168
	global_load_lds_dwordx4 v[194:195], off
	v_lshl_add_u64 v[194:195], s[4:5], 0, v[140:141]
	s_add_i32 m0, s7, 0xe000
	s_nop 0
	global_load_lds_dwordx4 v[194:195], off
	s_waitcnt lgkmcnt(8)
	s_barrier
	s_waitcnt lgkmcnt(0)
	s_waitcnt lgkmcnt(0)
	v_mfma_f32_16x16x32_bf16 v[126:129], v[142:145], v[160:163], v[126:129]
	v_mfma_f32_16x16x32_bf16 v[122:125], v[152:155], v[160:163], v[122:125]
	v_mfma_f32_16x16x32_bf16 v[110:113], v[142:145], v[168:171], v[110:113]
	v_mfma_f32_16x16x32_bf16 v[106:109], v[152:155], v[168:171], v[106:109]
	v_mfma_f32_16x16x32_bf16 v[94:97], v[142:145], v[176:179], v[94:97]
	v_mfma_f32_16x16x32_bf16 v[90:93], v[152:155], v[176:179], v[90:93]
	v_mfma_f32_16x16x32_bf16 v[78:81], v[142:145], v[184:187], v[78:81]
	v_mfma_f32_16x16x32_bf16 v[74:77], v[152:155], v[184:187], v[74:77]
	v_mfma_f32_16x16x32_bf16 v[126:129], v[146:149], v[164:167], v[126:129]
	v_mfma_f32_16x16x32_bf16 v[122:125], v[156:159], v[164:167], v[122:125]
	v_mfma_f32_16x16x32_bf16 v[110:113], v[146:149], v[172:175], v[110:113]
	v_mfma_f32_16x16x32_bf16 v[106:109], v[156:159], v[172:175], v[106:109]
	v_mfma_f32_16x16x32_bf16 v[94:97], v[146:149], v[180:183], v[94:97]
	v_mfma_f32_16x16x32_bf16 v[90:93], v[156:159], v[180:183], v[90:93]
	v_mfma_f32_16x16x32_bf16 v[78:81], v[146:149], v[190:193], v[78:81]
	v_mfma_f32_16x16x32_bf16 v[74:77], v[156:159], v[190:193], v[74:77]
	s_barrier
	s_add_i32 s88, 0, 0x14000
	s_add_i32 s86, s86, s22
	v_add_u32_e32 v0, s88, v150
	v_lshl_add_u64 v[210:211], s[12:13], 0, v[134:135]
	s_mov_b32 m0, s86
	ds_read_b128 v[194:197], v0
	ds_read_b128 v[198:201], v0 offset:1024
	ds_read_b128 v[202:205], v0 offset:2048
	ds_read_b128 v[206:209], v0 offset:3072
	global_load_lds_dwordx4 v[210:211], off
	v_lshl_add_u64 v[212:213], s[12:13], 0, v[130:131]
	s_add_i32 m0, s86, 0x2000
	s_nop 0
	global_load_lds_dwordx4 v[212:213], off
	s_barrier
	s_waitcnt lgkmcnt(0)
	s_waitcnt lgkmcnt(0)
	v_mfma_f32_16x16x32_bf16 v[118:121], v[194:197], v[160:163], v[118:121]
	v_mfma_f32_16x16x32_bf16 v[114:117], v[202:205], v[160:163], v[114:117]
	v_mfma_f32_16x16x32_bf16 v[102:105], v[194:197], v[168:171], v[102:105]
	v_mfma_f32_16x16x32_bf16 v[98:101], v[202:205], v[168:171], v[98:101]
	v_mfma_f32_16x16x32_bf16 v[86:89], v[194:197], v[176:179], v[86:89]
	v_mfma_f32_16x16x32_bf16 v[82:85], v[202:205], v[176:179], v[82:85]
	v_mfma_f32_16x16x32_bf16 v[70:73], v[194:197], v[184:187], v[70:73]
	v_mfma_f32_16x16x32_bf16 v[66:69], v[202:205], v[184:187], v[66:69]
	v_mfma_f32_16x16x32_bf16 v[118:121], v[198:201], v[164:167], v[118:121]
	v_mfma_f32_16x16x32_bf16 v[114:117], v[206:209], v[164:167], v[114:117]
	v_mfma_f32_16x16x32_bf16 v[102:105], v[198:201], v[172:175], v[102:105]
	v_mfma_f32_16x16x32_bf16 v[98:101], v[206:209], v[172:175], v[98:101]
	v_mfma_f32_16x16x32_bf16 v[86:89], v[198:201], v[180:183], v[86:89]
	v_mfma_f32_16x16x32_bf16 v[82:85], v[206:209], v[180:183], v[82:85]
	v_mfma_f32_16x16x32_bf16 v[70:73], v[198:201], v[190:193], v[70:73]
	v_mfma_f32_16x16x32_bf16 v[66:69], v[206:209], v[190:193], v[66:69]
	s_mov_b32 m0, s7
	v_lshl_add_u64 v[214:215], s[14:15], 0, v[136:137]
	s_barrier
	ds_read_b128 v[160:163], v151 offset:16384
	ds_read_b128 v[164:167], v151 offset:17408
	ds_read_b128 v[168:171], v151 offset:18432
	ds_read_b128 v[172:175], v151 offset:19456
	ds_read_b128 v[176:179], v151 offset:20480
	ds_read_b128 v[180:183], v151 offset:21504
	ds_read_b128 v[184:187], v151 offset:22528
	ds_read_b128 v[190:193], v151 offset:23552
	global_load_lds_dwordx4 v[214:215], off
	v_lshl_add_u64 v[216:217], s[14:15], 0, v[132:133]
	s_mov_b32 m0, s23
	s_nop 0
	global_load_lds_dwordx4 v[216:217], off
	s_barrier
	s_waitcnt lgkmcnt(0)
	s_waitcnt lgkmcnt(0)
	v_mfma_f32_16x16x32_bf16 v[62:65], v[142:145], v[160:163], v[62:65]
	v_mfma_f32_16x16x32_bf16 v[58:61], v[152:155], v[160:163], v[58:61]
	v_mfma_f32_16x16x32_bf16 v[46:49], v[142:145], v[168:171], v[46:49]
	v_mfma_f32_16x16x32_bf16 v[42:45], v[152:155], v[168:171], v[42:45]
	v_mfma_f32_16x16x32_bf16 v[30:33], v[142:145], v[176:179], v[30:33]
	v_mfma_f32_16x16x32_bf16 v[26:29], v[152:155], v[176:179], v[26:29]
	v_mfma_f32_16x16x32_bf16 v[14:17], v[142:145], v[184:187], v[14:17]
	v_mfma_f32_16x16x32_bf16 v[10:13], v[152:155], v[184:187], v[10:13]
	v_mfma_f32_16x16x32_bf16 v[62:65], v[146:149], v[164:167], v[62:65]
	v_mfma_f32_16x16x32_bf16 v[58:61], v[156:159], v[164:167], v[58:61]
	v_mfma_f32_16x16x32_bf16 v[46:49], v[146:149], v[172:175], v[46:49]
	v_mfma_f32_16x16x32_bf16 v[42:45], v[156:159], v[172:175], v[42:45]
	v_mfma_f32_16x16x32_bf16 v[30:33], v[146:149], v[180:183], v[30:33]
	v_mfma_f32_16x16x32_bf16 v[26:29], v[156:159], v[180:183], v[26:29]
	v_mfma_f32_16x16x32_bf16 v[14:17], v[146:149], v[190:193], v[14:17]
	v_mfma_f32_16x16x32_bf16 v[10:13], v[156:159], v[190:193], v[10:13]
	s_barrier
	s_add_u32 s86, s12, 0x40000
	s_addc_u32 s87, s13, 0
	s_add_i32 s88, s88, s22
	v_lshl_add_u64 v[142:143], s[86:87], 0, v[134:135]
	s_mov_b32 m0, s88
	s_nop 0
	global_load_lds_dwordx4 v[142:143], off
	v_lshl_add_u64 v[142:143], s[86:87], 0, v[130:131]
	s_add_i32 m0, s88, 0x2000
	s_nop 0
	global_load_lds_dwordx4 v[142:143], off
	s_waitcnt vmcnt(6)
	s_barrier
	v_mfma_f32_16x16x32_bf16 v[54:57], v[194:197], v[160:163], v[54:57]
	v_mfma_f32_16x16x32_bf16 v[50:53], v[202:205], v[160:163], v[50:53]
	v_mfma_f32_16x16x32_bf16 v[38:41], v[194:197], v[168:171], v[38:41]
	v_mfma_f32_16x16x32_bf16 v[34:37], v[202:205], v[168:171], v[34:37]
	v_mfma_f32_16x16x32_bf16 v[22:25], v[194:197], v[176:179], v[22:25]
	v_mfma_f32_16x16x32_bf16 v[18:21], v[202:205], v[176:179], v[18:21]
	v_mfma_f32_16x16x32_bf16 v[6:9], v[194:197], v[184:187], v[6:9]
	v_mfma_f32_16x16x32_bf16 v[2:5], v[202:205], v[184:187], v[2:5]
	v_mfma_f32_16x16x32_bf16 v[54:57], v[198:201], v[164:167], v[54:57]
	v_mfma_f32_16x16x32_bf16 v[50:53], v[206:209], v[164:167], v[50:53]
	v_mfma_f32_16x16x32_bf16 v[38:41], v[198:201], v[172:175], v[38:41]
	v_mfma_f32_16x16x32_bf16 v[34:37], v[206:209], v[172:175], v[34:37]
	v_mfma_f32_16x16x32_bf16 v[22:25], v[198:201], v[180:183], v[22:25]
	v_mfma_f32_16x16x32_bf16 v[18:21], v[206:209], v[180:183], v[18:21]
	v_mfma_f32_16x16x32_bf16 v[6:9], v[198:201], v[190:193], v[6:9]
	v_mfma_f32_16x16x32_bf16 v[2:5], v[206:209], v[190:193], v[2:5]
	s_add_i32 s86, 0, 0x18000
	v_add_u32_e32 v0, s86, v150
	s_barrier
	ds_read_b128 v[142:145], v0
	ds_read_b128 v[146:149], v0 offset:1024
	ds_read_b128 v[152:155], v0 offset:2048
	ds_read_b128 v[156:159], v0 offset:3072
	s_add_u32 s14, s14, 0x40000
	s_addc_u32 s15, s15, 0
	s_mov_b32 m0, s28
	v_lshl_add_u64 v[194:195], s[14:15], 0, v[136:137]
	ds_read_b128 v[160:163], v151 offset:32768
	ds_read_b128 v[164:167], v151 offset:33792
	ds_read_b128 v[168:171], v151 offset:34816
	ds_read_b128 v[172:175], v151 offset:35840
	ds_read_b128 v[176:179], v151 offset:36864
	ds_read_b128 v[180:183], v151 offset:37888
	ds_read_b128 v[184:187], v151 offset:38912
	ds_read_b128 v[190:193], v151 offset:39936
	global_load_lds_dwordx4 v[194:195], off
	v_lshl_add_u64 v[194:195], s[14:15], 0, v[132:133]
	s_mov_b32 m0, s29
	s_nop 0
	global_load_lds_dwordx4 v[194:195], off
	s_waitcnt lgkmcnt(8)
	s_barrier
	s_waitcnt lgkmcnt(0)
	s_waitcnt lgkmcnt(0)
	v_mfma_f32_16x16x32_bf16 v[126:129], v[142:145], v[160:163], v[126:129]
	v_mfma_f32_16x16x32_bf16 v[122:125], v[152:155], v[160:163], v[122:125]
	v_mfma_f32_16x16x32_bf16 v[110:113], v[142:145], v[168:171], v[110:113]
	v_mfma_f32_16x16x32_bf16 v[106:109], v[152:155], v[168:171], v[106:109]
	v_mfma_f32_16x16x32_bf16 v[94:97], v[142:145], v[176:179], v[94:97]
	v_mfma_f32_16x16x32_bf16 v[90:93], v[152:155], v[176:179], v[90:93]
	v_mfma_f32_16x16x32_bf16 v[78:81], v[142:145], v[184:187], v[78:81]
	v_mfma_f32_16x16x32_bf16 v[74:77], v[152:155], v[184:187], v[74:77]
	v_mfma_f32_16x16x32_bf16 v[126:129], v[146:149], v[164:167], v[126:129]
	v_mfma_f32_16x16x32_bf16 v[122:125], v[156:159], v[164:167], v[122:125]
	v_mfma_f32_16x16x32_bf16 v[110:113], v[146:149], v[172:175], v[110:113]
	v_mfma_f32_16x16x32_bf16 v[106:109], v[156:159], v[172:175], v[106:109]
	v_mfma_f32_16x16x32_bf16 v[94:97], v[146:149], v[180:183], v[94:97]
	v_mfma_f32_16x16x32_bf16 v[90:93], v[156:159], v[180:183], v[90:93]
	v_mfma_f32_16x16x32_bf16 v[78:81], v[146:149], v[190:193], v[78:81]
	v_mfma_f32_16x16x32_bf16 v[74:77], v[156:159], v[190:193], v[74:77]
	s_barrier
	s_add_i32 s14, 0, 0x1c000
	s_add_i32 s15, s86, s22
	v_add_u32_e32 v0, s14, v150
	v_lshl_add_u64 v[210:211], v[210:211], 0, s[40:41]
	s_mov_b32 m0, s15
	ds_read_b128 v[194:197], v0
	ds_read_b128 v[198:201], v0 offset:1024
	ds_read_b128 v[202:205], v0 offset:2048
	ds_read_b128 v[206:209], v0 offset:3072
	global_load_lds_dwordx4 v[210:211], off
	v_lshl_add_u64 v[210:211], v[212:213], 0, s[40:41]
	s_add_i32 m0, s15, 0x2000
	s_nop 0
	global_load_lds_dwordx4 v[210:211], off
	s_barrier
	s_waitcnt lgkmcnt(0)
	s_waitcnt lgkmcnt(0)
	v_mfma_f32_16x16x32_bf16 v[118:121], v[194:197], v[160:163], v[118:121]
	v_mfma_f32_16x16x32_bf16 v[114:117], v[202:205], v[160:163], v[114:117]
	v_mfma_f32_16x16x32_bf16 v[102:105], v[194:197], v[168:171], v[102:105]
	v_mfma_f32_16x16x32_bf16 v[98:101], v[202:205], v[168:171], v[98:101]
	v_mfma_f32_16x16x32_bf16 v[86:89], v[194:197], v[176:179], v[86:89]
	v_mfma_f32_16x16x32_bf16 v[82:85], v[202:205], v[176:179], v[82:85]
	v_mfma_f32_16x16x32_bf16 v[70:73], v[194:197], v[184:187], v[70:73]
	v_mfma_f32_16x16x32_bf16 v[66:69], v[202:205], v[184:187], v[66:69]
	v_mfma_f32_16x16x32_bf16 v[118:121], v[198:201], v[164:167], v[118:121]
	v_mfma_f32_16x16x32_bf16 v[114:117], v[206:209], v[164:167], v[114:117]
	v_mfma_f32_16x16x32_bf16 v[102:105], v[198:201], v[172:175], v[102:105]
	v_mfma_f32_16x16x32_bf16 v[98:101], v[206:209], v[172:175], v[98:101]
	v_mfma_f32_16x16x32_bf16 v[86:89], v[198:201], v[180:183], v[86:89]
	v_mfma_f32_16x16x32_bf16 v[82:85], v[206:209], v[180:183], v[82:85]
	v_mfma_f32_16x16x32_bf16 v[70:73], v[198:201], v[190:193], v[70:73]
	v_mfma_f32_16x16x32_bf16 v[66:69], v[206:209], v[190:193], v[66:69]
	s_mov_b32 m0, s38
	v_lshl_add_u64 v[210:211], v[214:215], 0, s[40:41]
	s_barrier
	ds_read_b128 v[160:163], v151 offset:49152
	ds_read_b128 v[164:167], v151 offset:50176
	ds_read_b128 v[168:171], v151 offset:51200
	ds_read_b128 v[172:175], v151 offset:52224
	ds_read_b128 v[176:179], v151 offset:53248
	ds_read_b128 v[180:183], v151 offset:54272
	ds_read_b128 v[184:187], v151 offset:55296
	ds_read_b128 v[190:193], v151 offset:56320
	global_load_lds_dwordx4 v[210:211], off
	v_lshl_add_u64 v[210:211], v[216:217], 0, s[40:41]
	s_mov_b32 m0, s39
	s_nop 0
	global_load_lds_dwordx4 v[210:211], off
	s_barrier
	s_waitcnt lgkmcnt(0)
	s_waitcnt lgkmcnt(0)
	v_mfma_f32_16x16x32_bf16 v[62:65], v[142:145], v[160:163], v[62:65]
	v_mfma_f32_16x16x32_bf16 v[58:61], v[152:155], v[160:163], v[58:61]
	v_mfma_f32_16x16x32_bf16 v[46:49], v[142:145], v[168:171], v[46:49]
	v_mfma_f32_16x16x32_bf16 v[42:45], v[152:155], v[168:171], v[42:45]
	v_mfma_f32_16x16x32_bf16 v[30:33], v[142:145], v[176:179], v[30:33]
	v_mfma_f32_16x16x32_bf16 v[26:29], v[152:155], v[176:179], v[26:29]
	v_mfma_f32_16x16x32_bf16 v[14:17], v[142:145], v[184:187], v[14:17]
	v_mfma_f32_16x16x32_bf16 v[10:13], v[152:155], v[184:187], v[10:13]
	v_mfma_f32_16x16x32_bf16 v[62:65], v[146:149], v[164:167], v[62:65]
	v_mfma_f32_16x16x32_bf16 v[58:61], v[156:159], v[164:167], v[58:61]
	v_mfma_f32_16x16x32_bf16 v[46:49], v[146:149], v[172:175], v[46:49]
	v_mfma_f32_16x16x32_bf16 v[42:45], v[156:159], v[172:175], v[42:45]
	v_mfma_f32_16x16x32_bf16 v[30:33], v[146:149], v[180:183], v[30:33]
	v_mfma_f32_16x16x32_bf16 v[26:29], v[156:159], v[180:183], v[26:29]
	v_mfma_f32_16x16x32_bf16 v[14:17], v[146:149], v[190:193], v[14:17]
	v_mfma_f32_16x16x32_bf16 v[10:13], v[156:159], v[190:193], v[10:13]
	s_barrier
	s_add_u32 s12, s12, 0x40080
	s_addc_u32 s13, s13, 0
	s_add_i32 s14, s14, s22
	v_lshl_add_u64 v[142:143], s[12:13], 0, v[134:135]
	s_mov_b32 m0, s14
	s_nop 0
	global_load_lds_dwordx4 v[142:143], off
	v_lshl_add_u64 v[142:143], s[12:13], 0, v[130:131]
	s_add_i32 m0, s14, 0x2000
	s_nop 0
	global_load_lds_dwordx4 v[142:143], off
	s_waitcnt vmcnt(6)
	s_barrier
	v_mfma_f32_16x16x32_bf16 v[54:57], v[194:197], v[160:163], v[54:57]
	v_mfma_f32_16x16x32_bf16 v[50:53], v[202:205], v[160:163], v[50:53]
	v_mfma_f32_16x16x32_bf16 v[38:41], v[194:197], v[168:171], v[38:41]
	v_mfma_f32_16x16x32_bf16 v[34:37], v[202:205], v[168:171], v[34:37]
	v_mfma_f32_16x16x32_bf16 v[22:25], v[194:197], v[176:179], v[22:25]
	v_mfma_f32_16x16x32_bf16 v[18:21], v[202:205], v[176:179], v[18:21]
	v_mfma_f32_16x16x32_bf16 v[6:9], v[194:197], v[184:187], v[6:9]
	v_mfma_f32_16x16x32_bf16 v[2:5], v[202:205], v[184:187], v[2:5]
	v_mfma_f32_16x16x32_bf16 v[54:57], v[198:201], v[164:167], v[54:57]
	v_mfma_f32_16x16x32_bf16 v[50:53], v[206:209], v[164:167], v[50:53]
	v_mfma_f32_16x16x32_bf16 v[38:41], v[198:201], v[172:175], v[38:41]
	v_mfma_f32_16x16x32_bf16 v[34:37], v[206:209], v[172:175], v[34:37]
	v_mfma_f32_16x16x32_bf16 v[22:25], v[198:201], v[180:183], v[22:25]
	v_mfma_f32_16x16x32_bf16 v[18:21], v[206:209], v[180:183], v[18:21]
	v_mfma_f32_16x16x32_bf16 v[6:9], v[198:201], v[190:193], v[6:9]
	v_mfma_f32_16x16x32_bf16 v[2:5], v[206:209], v[190:193], v[2:5]
	s_add_i32 s85, s85, 2
	s_add_u32 s4, s4, 0x100
	s_addc_u32 s5, s5, 0
	s_add_u32 s78, s78, 0x100
	s_addc_u32 s79, s79, 0
	s_cmp_gt_u32 s85, 13
	s_barrier
	s_cbranch_scc0 .LBB0_267
	v_mov_b32_e32 v156, v252
	s_mov_b64 s[4:5], -1
	v_and_b32_e32 v154, 63, v156
	s_andn2_b64 vcc, exec, s[2:3]
	v_lshlrev_b32_e32 v142, 2, v154
	s_cbranch_vccnz .LBB0_270
	v_lshlrev_b32_e32 v155, 2, v154
	s_mov_b64 s[4:5], 0

.LBB0_838:
	s_add_u32 s4, s88, 0x100
	s_addc_u32 s5, s89, 0
	s_add_i32 s79, 0, 0x10000
	v_add_u32_e32 v142, s79, v212
	ds_read_b128 v[130:133], v142
	ds_read_b128 v[134:137], v142 offset:1024
	ds_read_b128 v[138:141], v142 offset:2048
	ds_read_b128 v[142:145], v142 offset:3072
	s_cmp_eq_u32 s78, 12
	s_cselect_b32 s93, s17, s5
	s_cselect_b32 s92, s16, s4
	s_cselect_b32 s91, s15, s75
	s_cselect_b32 s90, s23, s34
	v_lshl_add_u64 v[178:179], s[88:89], 0, v[196:197]
	s_add_i32 m0, s39, 0xc000
	ds_read_b128 v[146:149], v213
	ds_read_b128 v[150:153], v213 offset:1024
	ds_read_b128 v[154:157], v213 offset:2048
	ds_read_b128 v[158:161], v213 offset:3072
	ds_read_b128 v[162:165], v213 offset:4096
	ds_read_b128 v[166:169], v213 offset:5120
	ds_read_b128 v[170:173], v213 offset:6144
	ds_read_b128 v[174:177], v213 offset:7168
	global_load_lds_dwordx4 v[178:179], off
	v_lshl_add_u64 v[178:179], s[88:89], 0, v[198:199]
	s_add_i32 m0, s39, 0xe000
	s_nop 0
	global_load_lds_dwordx4 v[178:179], off
	s_waitcnt lgkmcnt(8)
	s_barrier
	s_waitcnt lgkmcnt(0)
	s_waitcnt lgkmcnt(0)
	v_mfma_f32_16x16x32_bf16 v[126:129], v[130:133], v[146:149], v[126:129]
	v_mfma_f32_16x16x32_bf16 v[122:125], v[138:141], v[146:149], v[122:125]
	v_mfma_f32_16x16x32_bf16 v[110:113], v[130:133], v[154:157], v[110:113]
	v_mfma_f32_16x16x32_bf16 v[106:109], v[138:141], v[154:157], v[106:109]
	v_mfma_f32_16x16x32_bf16 v[94:97], v[130:133], v[162:165], v[94:97]
	v_mfma_f32_16x16x32_bf16 v[90:93], v[138:141], v[162:165], v[90:93]
	v_mfma_f32_16x16x32_bf16 v[78:81], v[130:133], v[170:173], v[78:81]
	v_mfma_f32_16x16x32_bf16 v[74:77], v[138:141], v[170:173], v[74:77]
	v_mfma_f32_16x16x32_bf16 v[126:129], v[134:137], v[150:153], v[126:129]
	v_mfma_f32_16x16x32_bf16 v[122:125], v[142:145], v[150:153], v[122:125]
	v_mfma_f32_16x16x32_bf16 v[110:113], v[134:137], v[158:161], v[110:113]
	v_mfma_f32_16x16x32_bf16 v[106:109], v[142:145], v[158:161], v[106:109]
	v_mfma_f32_16x16x32_bf16 v[94:97], v[134:137], v[166:169], v[94:97]
	v_mfma_f32_16x16x32_bf16 v[90:93], v[142:145], v[166:169], v[90:93]
	v_mfma_f32_16x16x32_bf16 v[78:81], v[134:137], v[174:177], v[78:81]
	v_mfma_f32_16x16x32_bf16 v[74:77], v[142:145], v[174:177], v[74:77]
	s_barrier
	s_add_i32 s87, 0, 0x14000
	v_add_u32_e32 v186, s87, v212
	s_add_i32 s79, s79, s38
	ds_read_b128 v[178:181], v186
	ds_read_b128 v[182:185], v186 offset:1024
	ds_read_b128 v[200:203], v186 offset:2048
	ds_read_b128 v[204:207], v186 offset:3072
	v_lshl_add_u64 v[186:187], s[90:91], 0, v[0:1]
	s_mov_b32 m0, s79
	v_lshl_add_u64 v[208:209], s[90:91], 0, v[194:195]
	global_load_lds_dwordx4 v[186:187], off
	s_add_i32 m0, s79, 0x2000
	s_nop 0
	global_load_lds_dwordx4 v[208:209], off
	s_barrier
	s_waitcnt lgkmcnt(0)
	s_waitcnt lgkmcnt(0)
	v_mfma_f32_16x16x32_bf16 v[118:121], v[178:181], v[146:149], v[118:121]
	v_mfma_f32_16x16x32_bf16 v[114:117], v[200:203], v[146:149], v[114:117]
	v_mfma_f32_16x16x32_bf16 v[102:105], v[178:181], v[154:157], v[102:105]
	v_mfma_f32_16x16x32_bf16 v[98:101], v[200:203], v[154:157], v[98:101]
	v_mfma_f32_16x16x32_bf16 v[86:89], v[178:181], v[162:165], v[86:89]
	v_mfma_f32_16x16x32_bf16 v[82:85], v[200:203], v[162:165], v[82:85]
	v_mfma_f32_16x16x32_bf16 v[70:73], v[178:181], v[170:173], v[70:73]
	v_mfma_f32_16x16x32_bf16 v[66:69], v[200:203], v[170:173], v[66:69]
	v_mfma_f32_16x16x32_bf16 v[118:121], v[182:185], v[150:153], v[118:121]
	v_mfma_f32_16x16x32_bf16 v[114:117], v[204:207], v[150:153], v[114:117]
	v_mfma_f32_16x16x32_bf16 v[102:105], v[182:185], v[158:161], v[102:105]
	v_mfma_f32_16x16x32_bf16 v[98:101], v[204:207], v[158:161], v[98:101]
	v_mfma_f32_16x16x32_bf16 v[86:89], v[182:185], v[166:169], v[86:89]
	v_mfma_f32_16x16x32_bf16 v[82:85], v[204:207], v[166:169], v[82:85]
	v_mfma_f32_16x16x32_bf16 v[70:73], v[182:185], v[174:177], v[70:73]
	v_mfma_f32_16x16x32_bf16 v[66:69], v[204:207], v[174:177], v[66:69]
	s_mov_b32 m0, s39
	v_lshl_add_u64 v[210:211], s[92:93], 0, v[190:191]
	s_barrier
	ds_read_b128 v[146:149], v213 offset:16384
	ds_read_b128 v[150:153], v213 offset:17408
	ds_read_b128 v[154:157], v213 offset:18432
	ds_read_b128 v[158:161], v213 offset:19456
	ds_read_b128 v[162:165], v213 offset:20480
	ds_read_b128 v[166:169], v213 offset:21504
	ds_read_b128 v[170:173], v213 offset:22528
	ds_read_b128 v[174:177], v213 offset:23552
	global_load_lds_dwordx4 v[210:211], off
	v_lshl_add_u64 v[214:215], s[92:93], 0, v[192:193]
	s_mov_b32 m0, s42
	s_nop 0
	global_load_lds_dwordx4 v[214:215], off
	s_barrier
	s_waitcnt lgkmcnt(0)
	s_waitcnt lgkmcnt(0)
	v_mfma_f32_16x16x32_bf16 v[62:65], v[130:133], v[146:149], v[62:65]
	v_mfma_f32_16x16x32_bf16 v[58:61], v[138:141], v[146:149], v[58:61]
	v_mfma_f32_16x16x32_bf16 v[46:49], v[130:133], v[154:157], v[46:49]
	v_mfma_f32_16x16x32_bf16 v[42:45], v[138:141], v[154:157], v[42:45]
	v_mfma_f32_16x16x32_bf16 v[30:33], v[130:133], v[162:165], v[30:33]
	v_mfma_f32_16x16x32_bf16 v[26:29], v[138:141], v[162:165], v[26:29]
	v_mfma_f32_16x16x32_bf16 v[14:17], v[130:133], v[170:173], v[14:17]
	v_mfma_f32_16x16x32_bf16 v[10:13], v[138:141], v[170:173], v[10:13]
	v_mfma_f32_16x16x32_bf16 v[62:65], v[134:137], v[150:153], v[62:65]
	v_mfma_f32_16x16x32_bf16 v[58:61], v[142:145], v[150:153], v[58:61]
	v_mfma_f32_16x16x32_bf16 v[46:49], v[134:137], v[158:161], v[46:49]
	v_mfma_f32_16x16x32_bf16 v[42:45], v[142:145], v[158:161], v[42:45]
	v_mfma_f32_16x16x32_bf16 v[30:33], v[134:137], v[166:169], v[30:33]
	v_mfma_f32_16x16x32_bf16 v[26:29], v[142:145], v[166:169], v[26:29]
	v_mfma_f32_16x16x32_bf16 v[14:17], v[134:137], v[174:177], v[14:17]
	v_mfma_f32_16x16x32_bf16 v[10:13], v[142:145], v[174:177], v[10:13]
	s_barrier
	s_add_u32 s88, s90, 0x40000
	s_addc_u32 s89, s91, 0
	s_add_i32 s79, s87, s38
	v_lshl_add_u64 v[130:131], s[88:89], 0, v[0:1]
	s_mov_b32 m0, s79
	s_nop 0
	global_load_lds_dwordx4 v[130:131], off
	v_lshl_add_u64 v[130:131], s[88:89], 0, v[194:195]
	s_add_i32 m0, s79, 0x2000
	s_nop 0
	global_load_lds_dwordx4 v[130:131], off
	s_waitcnt vmcnt(6)
	s_barrier
	v_mfma_f32_16x16x32_bf16 v[54:57], v[178:181], v[146:149], v[54:57]
	v_mfma_f32_16x16x32_bf16 v[50:53], v[200:203], v[146:149], v[50:53]
	v_mfma_f32_16x16x32_bf16 v[38:41], v[178:181], v[154:157], v[38:41]
	v_mfma_f32_16x16x32_bf16 v[34:37], v[200:203], v[154:157], v[34:37]
	v_mfma_f32_16x16x32_bf16 v[22:25], v[178:181], v[162:165], v[22:25]
	v_mfma_f32_16x16x32_bf16 v[18:21], v[200:203], v[162:165], v[18:21]
	v_mfma_f32_16x16x32_bf16 v[6:9], v[178:181], v[170:173], v[6:9]
	v_mfma_f32_16x16x32_bf16 v[2:5], v[200:203], v[170:173], v[2:5]
	v_mfma_f32_16x16x32_bf16 v[54:57], v[182:185], v[150:153], v[54:57]
	v_mfma_f32_16x16x32_bf16 v[50:53], v[204:207], v[150:153], v[50:53]
	v_mfma_f32_16x16x32_bf16 v[38:41], v[182:185], v[158:161], v[38:41]
	v_mfma_f32_16x16x32_bf16 v[34:37], v[204:207], v[158:161], v[34:37]
	v_mfma_f32_16x16x32_bf16 v[22:25], v[182:185], v[166:169], v[22:25]
	v_mfma_f32_16x16x32_bf16 v[18:21], v[204:207], v[166:169], v[18:21]
	v_mfma_f32_16x16x32_bf16 v[6:9], v[182:185], v[174:177], v[6:9]
	v_mfma_f32_16x16x32_bf16 v[2:5], v[204:207], v[174:177], v[2:5]
	s_add_i32 s79, 0, 0x18000
	v_add_u32_e32 v142, s79, v212
	s_barrier
	ds_read_b128 v[130:133], v142
	ds_read_b128 v[134:137], v142 offset:1024
	ds_read_b128 v[138:141], v142 offset:2048
	ds_read_b128 v[142:145], v142 offset:3072
	s_add_u32 s88, s92, 0xc0000
	s_addc_u32 s89, s93, 0
	s_mov_b32 m0, s43
	v_lshl_add_u64 v[178:179], s[88:89], 0, v[190:191]
	ds_read_b128 v[146:149], v213 offset:32768
	ds_read_b128 v[150:153], v213 offset:33792
	ds_read_b128 v[154:157], v213 offset:34816
	ds_read_b128 v[158:161], v213 offset:35840
	ds_read_b128 v[162:165], v213 offset:36864
	ds_read_b128 v[166:169], v213 offset:37888
	ds_read_b128 v[170:173], v213 offset:38912
	ds_read_b128 v[174:177], v213 offset:39936
	global_load_lds_dwordx4 v[178:179], off
	v_lshl_add_u64 v[178:179], s[88:89], 0, v[192:193]
	s_mov_b32 m0, s44
	s_nop 0
	global_load_lds_dwordx4 v[178:179], off
	s_waitcnt lgkmcnt(8)
	s_barrier
	s_waitcnt lgkmcnt(0)
	s_waitcnt lgkmcnt(0)
	v_mfma_f32_16x16x32_bf16 v[126:129], v[130:133], v[146:149], v[126:129]
	v_mfma_f32_16x16x32_bf16 v[122:125], v[138:141], v[146:149], v[122:125]
	v_mfma_f32_16x16x32_bf16 v[110:113], v[130:133], v[154:157], v[110:113]
	v_mfma_f32_16x16x32_bf16 v[106:109], v[138:141], v[154:157], v[106:109]
	v_mfma_f32_16x16x32_bf16 v[94:97], v[130:133], v[162:165], v[94:97]
	v_mfma_f32_16x16x32_bf16 v[90:93], v[138:141], v[162:165], v[90:93]
	v_mfma_f32_16x16x32_bf16 v[78:81], v[130:133], v[170:173], v[78:81]
	v_mfma_f32_16x16x32_bf16 v[74:77], v[138:141], v[170:173], v[74:77]
	v_mfma_f32_16x16x32_bf16 v[126:129], v[134:137], v[150:153], v[126:129]
	v_mfma_f32_16x16x32_bf16 v[122:125], v[142:145], v[150:153], v[122:125]
	v_mfma_f32_16x16x32_bf16 v[110:113], v[134:137], v[158:161], v[110:113]
	v_mfma_f32_16x16x32_bf16 v[106:109], v[142:145], v[158:161], v[106:109]
	v_mfma_f32_16x16x32_bf16 v[94:97], v[134:137], v[166:169], v[94:97]
	v_mfma_f32_16x16x32_bf16 v[90:93], v[142:145], v[166:169], v[90:93]
	v_mfma_f32_16x16x32_bf16 v[78:81], v[134:137], v[174:177], v[78:81]
	v_mfma_f32_16x16x32_bf16 v[74:77], v[142:145], v[174:177], v[74:77]
	s_barrier
	s_add_i32 s87, 0, 0x1c000
	s_add_i32 s79, s79, s38
	v_add_u32_e32 v204, s87, v212
	v_lshl_add_u64 v[186:187], v[186:187], 0, s[40:41]
	s_mov_b32 m0, s79
	ds_read_b128 v[178:181], v204
	ds_read_b128 v[182:185], v204 offset:1024
	ds_read_b128 v[200:203], v204 offset:2048
	ds_read_b128 v[204:207], v204 offset:3072
	global_load_lds_dwordx4 v[186:187], off
	v_lshl_add_u64 v[186:187], v[208:209], 0, s[40:41]
	s_add_i32 m0, s79, 0x2000
	s_nop 0
	global_load_lds_dwordx4 v[186:187], off
	s_barrier
	s_waitcnt lgkmcnt(0)
	s_waitcnt lgkmcnt(0)
	v_mfma_f32_16x16x32_bf16 v[118:121], v[178:181], v[146:149], v[118:121]
	v_mfma_f32_16x16x32_bf16 v[114:117], v[200:203], v[146:149], v[114:117]
	v_mfma_f32_16x16x32_bf16 v[102:105], v[178:181], v[154:157], v[102:105]
	v_mfma_f32_16x16x32_bf16 v[98:101], v[200:203], v[154:157], v[98:101]
	v_mfma_f32_16x16x32_bf16 v[86:89], v[178:181], v[162:165], v[86:89]
	v_mfma_f32_16x16x32_bf16 v[82:85], v[200:203], v[162:165], v[82:85]
	v_mfma_f32_16x16x32_bf16 v[70:73], v[178:181], v[170:173], v[70:73]
	v_mfma_f32_16x16x32_bf16 v[66:69], v[200:203], v[170:173], v[66:69]
	v_mfma_f32_16x16x32_bf16 v[118:121], v[182:185], v[150:153], v[118:121]
	v_mfma_f32_16x16x32_bf16 v[114:117], v[204:207], v[150:153], v[114:117]
	v_mfma_f32_16x16x32_bf16 v[102:105], v[182:185], v[158:161], v[102:105]
	v_mfma_f32_16x16x32_bf16 v[98:101], v[204:207], v[158:161], v[98:101]
	v_mfma_f32_16x16x32_bf16 v[86:89], v[182:185], v[166:169], v[86:89]
	v_mfma_f32_16x16x32_bf16 v[82:85], v[204:207], v[166:169], v[82:85]
	v_mfma_f32_16x16x32_bf16 v[70:73], v[182:185], v[174:177], v[70:73]
	v_mfma_f32_16x16x32_bf16 v[66:69], v[204:207], v[174:177], v[66:69]
	s_mov_b32 m0, s60
	v_lshl_add_u64 v[186:187], v[210:211], 0, s[40:41]
	s_barrier
	ds_read_b128 v[146:149], v213 offset:49152
	ds_read_b128 v[150:153], v213 offset:50176
	ds_read_b128 v[154:157], v213 offset:51200
	ds_read_b128 v[158:161], v213 offset:52224
	ds_read_b128 v[162:165], v213 offset:53248
	ds_read_b128 v[166:169], v213 offset:54272
	ds_read_b128 v[170:173], v213 offset:55296
	ds_read_b128 v[174:177], v213 offset:56320
	global_load_lds_dwordx4 v[186:187], off
	v_lshl_add_u64 v[186:187], v[214:215], 0, s[40:41]
	s_mov_b32 m0, s61
	s_nop 0
	global_load_lds_dwordx4 v[186:187], off
	s_barrier
	s_waitcnt lgkmcnt(0)
	s_waitcnt lgkmcnt(0)
	v_mfma_f32_16x16x32_bf16 v[62:65], v[130:133], v[146:149], v[62:65]
	v_mfma_f32_16x16x32_bf16 v[58:61], v[138:141], v[146:149], v[58:61]
	v_mfma_f32_16x16x32_bf16 v[46:49], v[130:133], v[154:157], v[46:49]
	v_mfma_f32_16x16x32_bf16 v[42:45], v[138:141], v[154:157], v[42:45]
	v_mfma_f32_16x16x32_bf16 v[30:33], v[130:133], v[162:165], v[30:33]
	v_mfma_f32_16x16x32_bf16 v[26:29], v[138:141], v[162:165], v[26:29]
	v_mfma_f32_16x16x32_bf16 v[14:17], v[130:133], v[170:173], v[14:17]
	v_mfma_f32_16x16x32_bf16 v[10:13], v[138:141], v[170:173], v[10:13]
	v_mfma_f32_16x16x32_bf16 v[62:65], v[134:137], v[150:153], v[62:65]
	v_mfma_f32_16x16x32_bf16 v[58:61], v[142:145], v[150:153], v[58:61]
	v_mfma_f32_16x16x32_bf16 v[46:49], v[134:137], v[158:161], v[46:49]
	v_mfma_f32_16x16x32_bf16 v[42:45], v[142:145], v[158:161], v[42:45]
	v_mfma_f32_16x16x32_bf16 v[30:33], v[134:137], v[166:169], v[30:33]
	v_mfma_f32_16x16x32_bf16 v[26:29], v[142:145], v[166:169], v[26:29]
	v_mfma_f32_16x16x32_bf16 v[14:17], v[134:137], v[174:177], v[14:17]
	v_mfma_f32_16x16x32_bf16 v[10:13], v[142:145], v[174:177], v[10:13]
	s_barrier
	s_add_u32 s88, s90, 0x40080
	s_addc_u32 s89, s91, 0
	s_add_i32 s79, s87, s38
	v_lshl_add_u64 v[130:131], s[88:89], 0, v[0:1]
	s_mov_b32 m0, s79
	s_nop 0
	global_load_lds_dwordx4 v[130:131], off
	v_lshl_add_u64 v[130:131], s[88:89], 0, v[194:195]
	s_add_i32 m0, s79, 0x2000
	s_nop 0
	global_load_lds_dwordx4 v[130:131], off
	s_waitcnt vmcnt(6)
	s_barrier
	v_mfma_f32_16x16x32_bf16 v[54:57], v[178:181], v[146:149], v[54:57]
	v_mfma_f32_16x16x32_bf16 v[50:53], v[200:203], v[146:149], v[50:53]
	v_mfma_f32_16x16x32_bf16 v[38:41], v[178:181], v[154:157], v[38:41]
	v_mfma_f32_16x16x32_bf16 v[34:37], v[200:203], v[154:157], v[34:37]
	v_mfma_f32_16x16x32_bf16 v[22:25], v[178:181], v[162:165], v[22:25]
	v_mfma_f32_16x16x32_bf16 v[18:21], v[200:203], v[162:165], v[18:21]
	v_mfma_f32_16x16x32_bf16 v[6:9], v[178:181], v[170:173], v[6:9]
	v_mfma_f32_16x16x32_bf16 v[2:5], v[200:203], v[170:173], v[2:5]
	v_mfma_f32_16x16x32_bf16 v[54:57], v[182:185], v[150:153], v[54:57]
	v_mfma_f32_16x16x32_bf16 v[50:53], v[204:207], v[150:153], v[50:53]
	v_mfma_f32_16x16x32_bf16 v[38:41], v[182:185], v[158:161], v[38:41]
	v_mfma_f32_16x16x32_bf16 v[34:37], v[204:207], v[158:161], v[34:37]
	v_mfma_f32_16x16x32_bf16 v[22:25], v[182:185], v[166:169], v[22:25]
	v_mfma_f32_16x16x32_bf16 v[18:21], v[204:207], v[166:169], v[18:21]
	v_mfma_f32_16x16x32_bf16 v[6:9], v[182:185], v[174:177], v[6:9]
	v_mfma_f32_16x16x32_bf16 v[2:5], v[204:207], v[174:177], v[2:5]
	s_add_i32 s78, s78, 2
	s_add_u32 s34, s34, 0x100
	s_addc_u32 s75, s75, 0
	s_cmp_gt_u32 s78, 13
	s_mov_b64 s[88:89], s[4:5]
	s_barrier
	s_cbranch_scc0 .LBB0_838
	s_lshl_b32 s4, s22, 8
	v_mov_b32_e32 v186, v252
	s_add_i32 s4, s4, s47
	s_nop 0
	v_and_or_b32 v202, v186, 15, s4
	s_lshl_b32 s4, s86, 8
	s_or_b32 s4, s4, s55
	v_lshrrev_b32_e32 v130, 1, v186
	v_and_or_b32 v200, v130, 24, s4
	v_ashrrev_i32_e32 v201, 31, v200
	v_ashrrev_i32_e32 v203, 31, v202
	v_lshl_add_u64 v[204:205], v[200:201], 2, s[6:7]
	v_lshlrev_b64 v[130:131], 12, v[202:203]
	v_lshl_add_u64 v[130:131], v[204:205], 0, v[130:131]
	global_load_dwordx4 v[216:219], v[130:131], off offset:16
	global_load_dwordx4 v[220:223], v[130:131], off
	global_load_dwordx4 v[178:181], v[130:131], off offset:528
	global_load_dwordx4 v[182:185], v[130:131], off offset:512
	v_or_b32_e32 v210, 16, v202
	v_ashrrev_i32_e32 v211, 31, v210
	v_lshlrev_b64 v[130:131], 12, v[210:211]
	v_or_b32_e32 v208, 32, v202
	v_lshl_add_u64 v[130:131], v[204:205], 0, v[130:131]
	v_ashrrev_i32_e32 v209, 31, v208
	global_load_dwordx4 v[170:173], v[130:131], off offset:16
	global_load_dwordx4 v[174:177], v[130:131], off
	global_load_dwordx4 v[162:165], v[130:131], off offset:528
	global_load_dwordx4 v[166:169], v[130:131], off offset:512
	v_lshlrev_b64 v[130:131], 12, v[208:209]
	v_or_b32_e32 v206, 48, v202
	v_lshl_add_u64 v[130:131], v[204:205], 0, v[130:131]
	v_ashrrev_i32_e32 v207, 31, v206
	global_load_dwordx4 v[154:157], v[130:131], off offset:16
	global_load_dwordx4 v[158:161], v[130:131], off
	global_load_dwordx4 v[138:141], v[130:131], off offset:528
	global_load_dwordx4 v[142:145], v[130:131], off offset:512
	v_lshlrev_b64 v[130:131], 12, v[206:207]
	v_lshl_add_u64 v[134:135], v[204:205], 0, v[130:131]
	global_load_dwordx4 v[146:149], v[134:135], off offset:16
	global_load_dwordx4 v[150:153], v[134:135], off
	global_load_dwordx4 v[130:133], v[134:135], off offset:528
	s_nop 0
	global_load_dwordx4 v[134:137], v[134:135], off offset:512
	v_and_b32_e32 v186, 63, v186
	v_lshlrev_b32_e32 v187, 2, v186
	v_xor_b32_e32 v215, 64, v187
	v_xor_b32_e32 v214, 0x80, v187
	v_cmp_gt_u32_e32 vcc, 16, v186
	v_lshlrev_b64 v[186:187], 10, v[202:203]
	v_lshl_add_u64 v[186:187], v[186:187], 0, v[200:201]
	s_lshl_b32 s4, s86, 2
	s_ashr_i32 s5, s4, 31
	s_waitcnt vmcnt(0)
	v_pk_add_f32 v[124:125], v[124:125], v[218:219]
	v_pk_add_f32 v[128:129], v[128:129], v[222:223]
	v_pk_add_f32 v[126:127], v[126:127], v[220:221]
	v_pk_mul_f32 v[218:219], v[128:129], v[128:129]
	v_pk_mul_f32 v[220:221], v[126:127], v[126:127]
	v_pk_add_f32 v[122:123], v[122:123], v[216:217]
	v_lshl_add_u64 v[216:217], v[186:187], 2, s[12:13]
	v_add_f32_e32 v220, v220, v221
	v_add_f32_e32 v218, v218, v219
	global_store_dwordx4 v[216:217], v[126:129], off
	global_store_dwordx4 v[216:217], v[122:125], off offset:16
	v_add_f32_e32 v222, v220, v218
	v_pk_mul_f32 v[220:221], v[122:123], v[122:123]
	v_cvt_pk_bf16_f32 v126, v126, v127
	v_cvt_pk_bf16_f32 v127, v128, v129
	v_cvt_pk_bf16_f32 v128, v122, v123
	v_cvt_pk_bf16_f32 v129, v124, v125
	v_lshl_add_u64 v[122:123], v[186:187], 1, s[8:9]
	v_pk_add_f32 v[120:121], v[120:121], v[184:185]
	v_pk_add_f32 v[118:119], v[118:119], v[182:183]
	v_pk_mul_f32 v[218:219], v[124:125], v[124:125]
	global_store_dwordx4 v[122:123], v[126:129], off
	v_pk_mul_f32 v[124:125], v[120:121], v[120:121]
	v_pk_add_f32 v[116:117], v[116:117], v[180:181]
	v_pk_mul_f32 v[126:127], v[118:119], v[118:119]
	v_pk_add_f32 v[114:115], v[114:115], v[178:179]
	v_add_f32_e32 v126, v126, v127
	v_add_f32_e32 v124, v124, v125
	v_add_f32_e32 v128, v126, v124
	v_pk_mul_f32 v[124:125], v[116:117], v[116:117]
	v_pk_mul_f32 v[126:127], v[114:115], v[114:115]
	v_add_f32_e32 v220, v220, v221
	v_add_f32_e32 v218, v218, v219
	v_add_f32_e32 v126, v126, v127
	v_add_f32_e32 v124, v124, v125
	v_add_f32_e32 v218, v220, v218
	v_add_f32_e32 v124, v126, v124
	v_add_f32_e32 v218, v222, v218
	v_add_f32_e32 v124, v128, v124
	v_add_f32_e32 v124, v218, v124
	global_store_dwordx4 v[216:217], v[118:121], off offset:512
	global_store_dwordx4 v[216:217], v[114:117], off offset:528
	s_nop 0
	v_cvt_pk_bf16_f32 v118, v118, v119
	v_cvt_pk_bf16_f32 v119, v120, v121
	v_cvt_pk_bf16_f32 v120, v114, v115
	ds_bpermute_b32 v114, v215, v124
	v_cvt_pk_bf16_f32 v121, v116, v117
	global_store_dwordx4 v[122:123], v[118:121], off offset:256
	s_waitcnt lgkmcnt(0)
	v_add_f32_e32 v114, v124, v114
	ds_bpermute_b32 v115, v214, v114
	s_and_saveexec_b64 s[22:23], vcc
	s_cbranch_execz .LBB0_841
	v_lshlrev_b64 v[116:117], 6, v[202:203]
	v_lshl_add_u64 v[116:117], s[10:11], 0, v[116:117]
	v_lshl_add_u64 v[116:117], s[4:5], 2, v[116:117]
	s_lshl_b32 s34, s45, 2
	v_lshl_add_u64 v[116:117], v[116:117], 0, s[34:35]
	s_waitcnt lgkmcnt(0)
	v_add_f32_e32 v114, v114, v115
	global_store_dword v[116:117], v114, off

.LBB0_919:
	s_add_u32 s88, s6, 0x100
	s_addc_u32 s89, s7, 0
	s_add_i32 vcc_lo, 0, 0x10000
	v_add_u32_e32 v0, vcc_lo, v254
	ds_read_b128 v[130:133], v0
	ds_read_b128 v[134:137], v0 offset:1024
	ds_read_b128 v[138:141], v0 offset:2048
	ds_read_b128 v[142:145], v0 offset:3072
	s_cmp_eq_u32 s45, 12
	s_cselect_b32 s93, s17, s89
	s_cselect_b32 s92, s22, s88
	s_cselect_b32 s91, s15, s29
	s_cselect_b32 s90, s23, s28
	v_lshl_add_u64 v[154:155], s[6:7], 0, v[164:165]
	s_add_i32 m0, s43, 0xc000
	ds_read_b128 v[146:149], v253
	ds_read_b128 v[150:153], v253 offset:1024
	ds_read_b128 v[168:171], v253 offset:2048
	ds_read_b128 v[172:175], v253 offset:3072
	ds_read_b128 v[176:179], v253 offset:4096
	ds_read_b128 v[180:183], v253 offset:5120
	ds_read_b128 v[184:187], v253 offset:6144
	ds_read_b128 v[190:193], v253 offset:7168
	global_load_lds_dwordx4 v[154:155], off
	v_lshl_add_u64 v[154:155], s[6:7], 0, v[166:167]
	s_add_i32 m0, s43, 0xe000
	s_nop 0
	global_load_lds_dwordx4 v[154:155], off
	s_waitcnt lgkmcnt(8)
	s_barrier
	s_waitcnt lgkmcnt(0)
	s_waitcnt lgkmcnt(0)
	v_mfma_f32_16x16x32_bf16 v[126:129], v[130:133], v[146:149], v[126:129]
	v_mfma_f32_16x16x32_bf16 v[70:73], v[138:141], v[146:149], v[70:73]
	v_mfma_f32_16x16x32_bf16 v[122:125], v[130:133], v[168:171], v[122:125]
	v_mfma_f32_16x16x32_bf16 v[74:77], v[138:141], v[168:171], v[74:77]
	v_mfma_f32_16x16x32_bf16 v[114:117], v[130:133], v[176:179], v[114:117]
	v_mfma_f32_16x16x32_bf16 v[66:69], v[138:141], v[176:179], v[66:69]
	v_mfma_f32_16x16x32_bf16 v[110:113], v[130:133], v[184:187], v[110:113]
	v_mfma_f32_16x16x32_bf16 v[78:81], v[138:141], v[184:187], v[78:81]
	v_mfma_f32_16x16x32_bf16 v[126:129], v[134:137], v[150:153], v[126:129]
	v_mfma_f32_16x16x32_bf16 v[70:73], v[142:145], v[150:153], v[70:73]
	v_mfma_f32_16x16x32_bf16 v[122:125], v[134:137], v[172:175], v[122:125]
	v_mfma_f32_16x16x32_bf16 v[74:77], v[142:145], v[172:175], v[74:77]
	v_mfma_f32_16x16x32_bf16 v[114:117], v[134:137], v[180:183], v[114:117]
	v_mfma_f32_16x16x32_bf16 v[66:69], v[142:145], v[180:183], v[66:69]
	v_mfma_f32_16x16x32_bf16 v[110:113], v[134:137], v[190:193], v[110:113]
	v_mfma_f32_16x16x32_bf16 v[78:81], v[142:145], v[190:193], v[78:81]
	s_barrier
	s_add_i32 vcc_hi, 0, 0x14000
	s_add_i32 s6, vcc_lo, s39
	v_add_u32_e32 v0, vcc_hi, v254
	v_lshl_add_u64 v[154:155], s[90:91], 0, v[160:161]
	s_mov_b32 m0, s6
	ds_read_b128 v[194:197], v0
	ds_read_b128 v[198:201], v0 offset:1024
	ds_read_b128 v[202:205], v0 offset:2048
	ds_read_b128 v[206:209], v0 offset:3072
	global_load_lds_dwordx4 v[154:155], off
	v_lshl_add_u64 v[210:211], s[90:91], 0, v[156:157]
	s_add_i32 m0, s6, 0x2000
	s_nop 0
	global_load_lds_dwordx4 v[210:211], off
	s_barrier
	s_waitcnt lgkmcnt(0)
	s_waitcnt lgkmcnt(0)
	v_mfma_f32_16x16x32_bf16 v[118:121], v[194:197], v[146:149], v[118:121]
	v_mfma_f32_16x16x32_bf16 v[94:97], v[202:205], v[146:149], v[94:97]
	v_mfma_f32_16x16x32_bf16 v[106:109], v[194:197], v[168:171], v[106:109]
	v_mfma_f32_16x16x32_bf16 v[90:93], v[202:205], v[168:171], v[90:93]
	v_mfma_f32_16x16x32_bf16 v[102:105], v[194:197], v[176:179], v[102:105]
	v_mfma_f32_16x16x32_bf16 v[82:85], v[202:205], v[176:179], v[82:85]
	v_mfma_f32_16x16x32_bf16 v[98:101], v[194:197], v[184:187], v[98:101]
	v_mfma_f32_16x16x32_bf16 v[86:89], v[202:205], v[184:187], v[86:89]
	v_mfma_f32_16x16x32_bf16 v[118:121], v[198:201], v[150:153], v[118:121]
	v_mfma_f32_16x16x32_bf16 v[94:97], v[206:209], v[150:153], v[94:97]
	v_mfma_f32_16x16x32_bf16 v[106:109], v[198:201], v[172:175], v[106:109]
	v_mfma_f32_16x16x32_bf16 v[90:93], v[206:209], v[172:175], v[90:93]
	v_mfma_f32_16x16x32_bf16 v[102:105], v[198:201], v[180:183], v[102:105]
	v_mfma_f32_16x16x32_bf16 v[82:85], v[206:209], v[180:183], v[82:85]
	v_mfma_f32_16x16x32_bf16 v[98:101], v[198:201], v[190:193], v[98:101]
	v_mfma_f32_16x16x32_bf16 v[86:89], v[206:209], v[190:193], v[86:89]
	s_mov_b32 m0, s43
	v_lshl_add_u64 v[212:213], s[92:93], 0, v[162:163]
	s_barrier
	ds_read_b128 v[146:149], v253 offset:16384
	ds_read_b128 v[150:153], v253 offset:17408
	ds_read_b128 v[168:171], v253 offset:18432
	ds_read_b128 v[172:175], v253 offset:19456
	ds_read_b128 v[176:179], v253 offset:20480
	ds_read_b128 v[180:183], v253 offset:21504
	ds_read_b128 v[184:187], v253 offset:22528
	ds_read_b128 v[190:193], v253 offset:23552
	global_load_lds_dwordx4 v[212:213], off
	v_lshl_add_u64 v[214:215], s[92:93], 0, v[158:159]
	s_mov_b32 m0, s60
	s_nop 0
	global_load_lds_dwordx4 v[214:215], off
	s_barrier
	s_waitcnt lgkmcnt(0)
	s_waitcnt lgkmcnt(0)
	v_mfma_f32_16x16x32_bf16 v[62:65], v[130:133], v[146:149], v[62:65]
	v_mfma_f32_16x16x32_bf16 v[10:13], v[138:141], v[146:149], v[10:13]
	v_mfma_f32_16x16x32_bf16 v[58:61], v[130:133], v[168:171], v[58:61]
	v_mfma_f32_16x16x32_bf16 v[14:17], v[138:141], v[168:171], v[14:17]
	v_mfma_f32_16x16x32_bf16 v[54:57], v[130:133], v[176:179], v[54:57]
	v_mfma_f32_16x16x32_bf16 v[6:9], v[138:141], v[176:179], v[6:9]
	v_mfma_f32_16x16x32_bf16 v[42:45], v[130:133], v[184:187], v[42:45]
	v_mfma_f32_16x16x32_bf16 v[2:5], v[138:141], v[184:187], v[2:5]
	v_mfma_f32_16x16x32_bf16 v[62:65], v[134:137], v[150:153], v[62:65]
	v_mfma_f32_16x16x32_bf16 v[10:13], v[142:145], v[150:153], v[10:13]
	v_mfma_f32_16x16x32_bf16 v[58:61], v[134:137], v[172:175], v[58:61]
	v_mfma_f32_16x16x32_bf16 v[14:17], v[142:145], v[172:175], v[14:17]
	v_mfma_f32_16x16x32_bf16 v[54:57], v[134:137], v[180:183], v[54:57]
	v_mfma_f32_16x16x32_bf16 v[6:9], v[142:145], v[180:183], v[6:9]
	v_mfma_f32_16x16x32_bf16 v[42:45], v[134:137], v[190:193], v[42:45]
	v_mfma_f32_16x16x32_bf16 v[2:5], v[142:145], v[190:193], v[2:5]
	s_barrier
	s_add_u32 s6, s90, 0x40000
	s_addc_u32 s7, s91, 0
	s_add_i32 vcc_lo, vcc_hi, s39
	v_lshl_add_u64 v[130:131], s[6:7], 0, v[160:161]
	s_mov_b32 m0, vcc_lo
	s_nop 0
	global_load_lds_dwordx4 v[130:131], off
	v_lshl_add_u64 v[130:131], s[6:7], 0, v[156:157]
	s_add_i32 m0, vcc_lo, 0x2000
	s_nop 0
	global_load_lds_dwordx4 v[130:131], off
	s_waitcnt vmcnt(6)
	s_barrier
	v_mfma_f32_16x16x32_bf16 v[50:53], v[194:197], v[146:149], v[50:53]
	v_mfma_f32_16x16x32_bf16 v[26:29], v[202:205], v[146:149], v[26:29]
	v_mfma_f32_16x16x32_bf16 v[46:49], v[194:197], v[168:171], v[46:49]
	v_mfma_f32_16x16x32_bf16 v[30:33], v[202:205], v[168:171], v[30:33]
	v_mfma_f32_16x16x32_bf16 v[38:41], v[194:197], v[176:179], v[38:41]
	v_mfma_f32_16x16x32_bf16 v[22:25], v[202:205], v[176:179], v[22:25]
	v_mfma_f32_16x16x32_bf16 v[34:37], v[194:197], v[184:187], v[34:37]
	v_mfma_f32_16x16x32_bf16 v[18:21], v[202:205], v[184:187], v[18:21]
	v_mfma_f32_16x16x32_bf16 v[50:53], v[198:201], v[150:153], v[50:53]
	v_mfma_f32_16x16x32_bf16 v[26:29], v[206:209], v[150:153], v[26:29]
	v_mfma_f32_16x16x32_bf16 v[46:49], v[198:201], v[172:175], v[46:49]
	v_mfma_f32_16x16x32_bf16 v[30:33], v[206:209], v[172:175], v[30:33]
	v_mfma_f32_16x16x32_bf16 v[38:41], v[198:201], v[180:183], v[38:41]
	v_mfma_f32_16x16x32_bf16 v[22:25], v[206:209], v[180:183], v[22:25]
	v_mfma_f32_16x16x32_bf16 v[34:37], v[198:201], v[190:193], v[34:37]
	v_mfma_f32_16x16x32_bf16 v[18:21], v[206:209], v[190:193], v[18:21]
	s_add_i32 vcc_lo, 0, 0x18000
	v_add_u32_e32 v0, vcc_lo, v254
	s_barrier
	ds_read_b128 v[130:133], v0
	ds_read_b128 v[134:137], v0 offset:1024
	ds_read_b128 v[138:141], v0 offset:2048
	ds_read_b128 v[142:145], v0 offset:3072
	s_add_u32 s6, s92, 0x40000
	s_addc_u32 s7, s93, 0
	s_mov_b32 m0, s61
	v_lshl_add_u64 v[194:195], s[6:7], 0, v[162:163]
	ds_read_b128 v[146:149], v253 offset:32768
	ds_read_b128 v[150:153], v253 offset:33792
	ds_read_b128 v[168:171], v253 offset:34816
	ds_read_b128 v[172:175], v253 offset:35840
	ds_read_b128 v[176:179], v253 offset:36864
	ds_read_b128 v[180:183], v253 offset:37888
	ds_read_b128 v[184:187], v253 offset:38912
	ds_read_b128 v[190:193], v253 offset:39936
	global_load_lds_dwordx4 v[194:195], off
	v_lshl_add_u64 v[194:195], s[6:7], 0, v[158:159]
	s_mov_b32 m0, s72
	s_nop 0
	global_load_lds_dwordx4 v[194:195], off
	s_waitcnt lgkmcnt(8)
	s_barrier
	s_waitcnt lgkmcnt(0)
	s_waitcnt lgkmcnt(0)
	v_mfma_f32_16x16x32_bf16 v[126:129], v[130:133], v[146:149], v[126:129]
	v_mfma_f32_16x16x32_bf16 v[70:73], v[138:141], v[146:149], v[70:73]
	v_mfma_f32_16x16x32_bf16 v[122:125], v[130:133], v[168:171], v[122:125]
	v_mfma_f32_16x16x32_bf16 v[74:77], v[138:141], v[168:171], v[74:77]
	v_mfma_f32_16x16x32_bf16 v[114:117], v[130:133], v[176:179], v[114:117]
	v_mfma_f32_16x16x32_bf16 v[66:69], v[138:141], v[176:179], v[66:69]
	v_mfma_f32_16x16x32_bf16 v[110:113], v[130:133], v[184:187], v[110:113]
	v_mfma_f32_16x16x32_bf16 v[78:81], v[138:141], v[184:187], v[78:81]
	v_mfma_f32_16x16x32_bf16 v[126:129], v[134:137], v[150:153], v[126:129]
	v_mfma_f32_16x16x32_bf16 v[70:73], v[142:145], v[150:153], v[70:73]
	v_mfma_f32_16x16x32_bf16 v[122:125], v[134:137], v[172:175], v[122:125]
	v_mfma_f32_16x16x32_bf16 v[74:77], v[142:145], v[172:175], v[74:77]
	v_mfma_f32_16x16x32_bf16 v[114:117], v[134:137], v[180:183], v[114:117]
	v_mfma_f32_16x16x32_bf16 v[66:69], v[142:145], v[180:183], v[66:69]
	v_mfma_f32_16x16x32_bf16 v[110:113], v[134:137], v[190:193], v[110:113]
	v_mfma_f32_16x16x32_bf16 v[78:81], v[142:145], v[190:193], v[78:81]
	s_barrier
	s_add_i32 s92, 0, 0x1c000
	s_add_i32 s6, vcc_lo, s39
	v_add_u32_e32 v0, s92, v254
	v_lshl_add_u64 v[154:155], v[154:155], 0, s[40:41]
	s_mov_b32 m0, s6
	ds_read_b128 v[194:197], v0
	ds_read_b128 v[198:201], v0 offset:1024
	ds_read_b128 v[202:205], v0 offset:2048
	ds_read_b128 v[206:209], v0 offset:3072
	global_load_lds_dwordx4 v[154:155], off
	v_lshl_add_u64 v[154:155], v[210:211], 0, s[40:41]
	s_add_i32 m0, s6, 0x2000
	s_nop 0
	global_load_lds_dwordx4 v[154:155], off
	s_barrier
	s_waitcnt lgkmcnt(0)
	s_waitcnt lgkmcnt(0)
	v_mfma_f32_16x16x32_bf16 v[118:121], v[194:197], v[146:149], v[118:121]
	v_mfma_f32_16x16x32_bf16 v[94:97], v[202:205], v[146:149], v[94:97]
	v_mfma_f32_16x16x32_bf16 v[106:109], v[194:197], v[168:171], v[106:109]
	v_mfma_f32_16x16x32_bf16 v[90:93], v[202:205], v[168:171], v[90:93]
	v_mfma_f32_16x16x32_bf16 v[102:105], v[194:197], v[176:179], v[102:105]
	v_mfma_f32_16x16x32_bf16 v[82:85], v[202:205], v[176:179], v[82:85]
	v_mfma_f32_16x16x32_bf16 v[98:101], v[194:197], v[184:187], v[98:101]
	v_mfma_f32_16x16x32_bf16 v[86:89], v[202:205], v[184:187], v[86:89]
	v_mfma_f32_16x16x32_bf16 v[118:121], v[198:201], v[150:153], v[118:121]
	v_mfma_f32_16x16x32_bf16 v[94:97], v[206:209], v[150:153], v[94:97]
	v_mfma_f32_16x16x32_bf16 v[106:109], v[198:201], v[172:175], v[106:109]
	v_mfma_f32_16x16x32_bf16 v[90:93], v[206:209], v[172:175], v[90:93]
	v_mfma_f32_16x16x32_bf16 v[102:105], v[198:201], v[180:183], v[102:105]
	v_mfma_f32_16x16x32_bf16 v[82:85], v[206:209], v[180:183], v[82:85]
	v_mfma_f32_16x16x32_bf16 v[98:101], v[198:201], v[190:193], v[98:101]
	v_mfma_f32_16x16x32_bf16 v[86:89], v[206:209], v[190:193], v[86:89]
	s_mov_b32 m0, s95
	v_lshl_add_u64 v[154:155], v[212:213], 0, s[40:41]
	s_barrier
	ds_read_b128 v[146:149], v253 offset:49152
	ds_read_b128 v[150:153], v253 offset:50176
	ds_read_b128 v[168:171], v253 offset:51200
	ds_read_b128 v[172:175], v253 offset:52224
	ds_read_b128 v[176:179], v253 offset:53248
	ds_read_b128 v[180:183], v253 offset:54272
	ds_read_b128 v[184:187], v253 offset:55296
	ds_read_b128 v[190:193], v253 offset:56320
	global_load_lds_dwordx4 v[154:155], off
	v_lshl_add_u64 v[154:155], v[214:215], 0, s[40:41]
	s_mov_b32 m0, s96
	s_nop 0
	global_load_lds_dwordx4 v[154:155], off
	s_barrier
	s_waitcnt lgkmcnt(0)
	s_waitcnt lgkmcnt(0)
	v_mfma_f32_16x16x32_bf16 v[62:65], v[130:133], v[146:149], v[62:65]
	v_mfma_f32_16x16x32_bf16 v[10:13], v[138:141], v[146:149], v[10:13]
	v_mfma_f32_16x16x32_bf16 v[58:61], v[130:133], v[168:171], v[58:61]
	v_mfma_f32_16x16x32_bf16 v[14:17], v[138:141], v[168:171], v[14:17]
	v_mfma_f32_16x16x32_bf16 v[54:57], v[130:133], v[176:179], v[54:57]
	v_mfma_f32_16x16x32_bf16 v[6:9], v[138:141], v[176:179], v[6:9]
	v_mfma_f32_16x16x32_bf16 v[42:45], v[130:133], v[184:187], v[42:45]
	v_mfma_f32_16x16x32_bf16 v[2:5], v[138:141], v[184:187], v[2:5]
	v_mfma_f32_16x16x32_bf16 v[62:65], v[134:137], v[150:153], v[62:65]
	v_mfma_f32_16x16x32_bf16 v[10:13], v[142:145], v[150:153], v[10:13]
	v_mfma_f32_16x16x32_bf16 v[58:61], v[134:137], v[172:175], v[58:61]
	v_mfma_f32_16x16x32_bf16 v[14:17], v[142:145], v[172:175], v[14:17]
	v_mfma_f32_16x16x32_bf16 v[54:57], v[134:137], v[180:183], v[54:57]
	v_mfma_f32_16x16x32_bf16 v[6:9], v[142:145], v[180:183], v[6:9]
	v_mfma_f32_16x16x32_bf16 v[42:45], v[134:137], v[190:193], v[42:45]
	v_mfma_f32_16x16x32_bf16 v[2:5], v[142:145], v[190:193], v[2:5]
	s_barrier
	s_add_u32 s6, s90, 0x40080
	s_addc_u32 s7, s91, 0
	s_add_i32 s90, s92, s39
	v_lshl_add_u64 v[130:131], s[6:7], 0, v[160:161]
	s_mov_b32 m0, s90
	s_nop 0
	global_load_lds_dwordx4 v[130:131], off
	v_lshl_add_u64 v[130:131], s[6:7], 0, v[156:157]
	s_add_i32 m0, s90, 0x2000
	s_nop 0
	global_load_lds_dwordx4 v[130:131], off
	s_waitcnt vmcnt(6)
	s_barrier
	v_mfma_f32_16x16x32_bf16 v[50:53], v[194:197], v[146:149], v[50:53]
	v_mfma_f32_16x16x32_bf16 v[26:29], v[202:205], v[146:149], v[26:29]
	v_mfma_f32_16x16x32_bf16 v[46:49], v[194:197], v[168:171], v[46:49]
	v_mfma_f32_16x16x32_bf16 v[30:33], v[202:205], v[168:171], v[30:33]
	v_mfma_f32_16x16x32_bf16 v[38:41], v[194:197], v[176:179], v[38:41]
	v_mfma_f32_16x16x32_bf16 v[22:25], v[202:205], v[176:179], v[22:25]
	v_mfma_f32_16x16x32_bf16 v[34:37], v[194:197], v[184:187], v[34:37]
	v_mfma_f32_16x16x32_bf16 v[18:21], v[202:205], v[184:187], v[18:21]
	v_mfma_f32_16x16x32_bf16 v[50:53], v[198:201], v[150:153], v[50:53]
	v_mfma_f32_16x16x32_bf16 v[26:29], v[206:209], v[150:153], v[26:29]
	v_mfma_f32_16x16x32_bf16 v[46:49], v[198:201], v[172:175], v[46:49]
	v_mfma_f32_16x16x32_bf16 v[30:33], v[206:209], v[172:175], v[30:33]
	v_mfma_f32_16x16x32_bf16 v[38:41], v[198:201], v[180:183], v[38:41]
	v_mfma_f32_16x16x32_bf16 v[22:25], v[206:209], v[180:183], v[22:25]
	v_mfma_f32_16x16x32_bf16 v[34:37], v[198:201], v[190:193], v[34:37]
	v_mfma_f32_16x16x32_bf16 v[18:21], v[206:209], v[190:193], v[18:21]
	s_add_i32 s45, s45, 2
	s_add_u32 s28, s28, 0x100
	s_addc_u32 s29, s29, 0
	s_cmp_gt_u32 s45, 13
	s_mov_b64 s[6:7], s[88:89]
	s_barrier
	s_cbranch_scc0 .LBB0_919
	v_mov_b32_e32 v131, v252
	s_lshl_b32 s88, s5, 7
	v_bfe_u32 v130, v131, 4, 2
	v_and_b32_e32 v134, 15, v131
	v_lshlrev_b32_e32 v0, 4, v130
	s_ashr_i32 s89, s88, 31
	s_lshl_b32 s15, s4, 8
	v_or3_b32 v135, v0, s97, v134
	s_lshl_b64 s[4:5], s[88:89], 2
	v_lshrrev_b32_e32 v140, 1, v135
	s_add_u32 s4, s73, s4
	s_addc_u32 s5, s74, s5
	v_lshlrev_b32_e32 v0, 2, v140
	v_and_b32_e32 v144, 1, v131
	v_lshl_add_u64 v[132:133], s[4:5], 0, v[0:1]
	v_cmp_eq_u32_e32 vcc, 1, v144
	v_mov_b32_e32 v0, 0xb00
	s_movk_i32 s4, 0x5000
	v_cndmask_b32_e32 v141, 0, v0, vcc
	v_lshlrev_b32_e32 v0, 2, v141
	v_lshl_add_u64 v[132:133], v[132:133], 0, v[0:1]
	v_add_co_u32_e32 v138, vcc, s4, v132
	s_mov_b32 s4, 0xb000
	s_nop 0
	v_addc_co_u32_e32 v139, vcc, 0, v133, vcc
	global_load_dword v136, v[132:133], off
	global_load_dword v137, v[138:139], off offset:2048
	v_add_co_u32_e32 v132, vcc, s4, v132
	v_add_u32_e32 v0, s88, v141
	s_nop 0
	v_addc_co_u32_e32 v133, vcc, 0, v133, vcc
	global_load_dword v138, v[132:133], off
	v_or_b32_e32 v132, v140, v0
	v_ashrrev_i32_e32 v133, 31, v132
	v_lshl_add_u64 v[132:133], v[132:133], 2, s[12:13]
	global_load_dword v139, v[132:133], off
	v_lshl_add_u32 v0, v135, 4, s78
	v_and_b32_e32 v135, 63, v131
	v_cmp_eq_u32_e32 vcc, 0, v144
	s_waitcnt vmcnt(0)
	ds_write_b128 v0, v[136:139]
	v_or_b32_e32 v0, s97, v135
	v_lshrrev_b32_e32 v0, 1, v0
	v_and_or_b32 v131, v0, 63, s55
	v_add_u32_e32 v132, s15, v131
	v_ashrrev_i32_e32 v133, 31, v132
	v_lshlrev_b64 v[132:133], 6, v[132:133]
	v_lshl_add_u64 v[132:133], s[10:11], 0, v[132:133]
	v_lshlrev_b32_e32 v0, 5, v144
	v_lshl_add_u64 v[132:133], v[132:133], 0, v[0:1]
	global_load_dwordx4 v[136:139], v[132:133], off offset:16
	global_load_dwordx4 v[140:143], v[132:133], off
	s_waitcnt vmcnt(0)
	v_add_f32_e32 v133, v138, v139
	v_add_f32_e32 v0, v140, v141
	v_add_f32_e32 v132, v142, v143
	v_add_f32_e32 v0, v0, v132
	v_add_f32_e32 v132, v136, v137
	v_add_f32_e32 v132, v132, v133
	v_add_f32_e32 v0, v0, v132
	v_lshlrev_b32_e32 v132, 2, v135
	v_xor_b32_e32 v132, 4, v132
	ds_bpermute_b32 v132, v132, v0
	s_and_saveexec_b64 s[4:5], vcc
	s_cbranch_execz .LBB0_922
	s_waitcnt lgkmcnt(0)
	v_add_f32_e32 v0, v0, v132
	v_mov_b32_e32 v132, 0x358637bd
	v_fmamk_f32 v0, v0, 0x3a800000, v132
	s_mov_b32 s6, 0x800000
	v_mul_f32_e32 v132, 0x4b800000, v0
	v_cmp_gt_f32_e32 vcc, s6, v0
	v_lshl_add_u32 v131, v131, 2, 0
	v_add_u32_e32 v131, 0x20000, v131
	v_cndmask_b32_e32 v0, v0, v132, vcc
	v_rsq_f32_e32 v0, v0
	s_nop 0
	v_mul_f32_e32 v132, 0x45800000, v0
	v_cndmask_b32_e32 v0, v0, v132, vcc
	ds_write_b32 v131, v0

.LBB0_1090:
	s_add_u32 s84, s16, 0x100
	s_addc_u32 s85, s17, 0
	s_add_i32 s90, 0, 0x10000
	v_add_u32_e32 v142, s90, v212
	ds_read_b128 v[130:133], v142
	ds_read_b128 v[134:137], v142 offset:1024
	ds_read_b128 v[138:141], v142 offset:2048
	ds_read_b128 v[142:145], v142 offset:3072
	s_cmp_eq_u32 s79, 40
	s_cselect_b32 s89, s5, s85
	s_cselect_b32 s88, s4, s84
	s_cselect_b32 s87, s7, s78
	s_cselect_b32 s86, s6, s34
	v_lshl_add_u64 v[178:179], s[16:17], 0, v[196:197]
	s_add_i32 m0, s39, 0xc000
	ds_read_b128 v[146:149], v213
	ds_read_b128 v[150:153], v213 offset:1024
	ds_read_b128 v[154:157], v213 offset:2048
	ds_read_b128 v[158:161], v213 offset:3072
	ds_read_b128 v[162:165], v213 offset:4096
	ds_read_b128 v[166:169], v213 offset:5120
	ds_read_b128 v[170:173], v213 offset:6144
	ds_read_b128 v[174:177], v213 offset:7168
	global_load_lds_dwordx4 v[178:179], off
	v_lshl_add_u64 v[178:179], s[16:17], 0, v[198:199]
	s_add_i32 m0, s39, 0xe000
	s_nop 0
	global_load_lds_dwordx4 v[178:179], off
	s_waitcnt lgkmcnt(8)
	s_barrier
	s_waitcnt lgkmcnt(0)
	s_waitcnt lgkmcnt(0)
	v_mfma_f32_16x16x32_bf16 v[126:129], v[130:133], v[146:149], v[126:129]
	v_mfma_f32_16x16x32_bf16 v[122:125], v[138:141], v[146:149], v[122:125]
	v_mfma_f32_16x16x32_bf16 v[110:113], v[130:133], v[154:157], v[110:113]
	v_mfma_f32_16x16x32_bf16 v[106:109], v[138:141], v[154:157], v[106:109]
	v_mfma_f32_16x16x32_bf16 v[94:97], v[130:133], v[162:165], v[94:97]
	v_mfma_f32_16x16x32_bf16 v[90:93], v[138:141], v[162:165], v[90:93]
	v_mfma_f32_16x16x32_bf16 v[78:81], v[130:133], v[170:173], v[78:81]
	v_mfma_f32_16x16x32_bf16 v[74:77], v[138:141], v[170:173], v[74:77]
	v_mfma_f32_16x16x32_bf16 v[126:129], v[134:137], v[150:153], v[126:129]
	v_mfma_f32_16x16x32_bf16 v[122:125], v[142:145], v[150:153], v[122:125]
	v_mfma_f32_16x16x32_bf16 v[110:113], v[134:137], v[158:161], v[110:113]
	v_mfma_f32_16x16x32_bf16 v[106:109], v[142:145], v[158:161], v[106:109]
	v_mfma_f32_16x16x32_bf16 v[94:97], v[134:137], v[166:169], v[94:97]
	v_mfma_f32_16x16x32_bf16 v[90:93], v[142:145], v[166:169], v[90:93]
	v_mfma_f32_16x16x32_bf16 v[78:81], v[134:137], v[174:177], v[78:81]
	v_mfma_f32_16x16x32_bf16 v[74:77], v[142:145], v[174:177], v[74:77]
	s_barrier
	s_add_i32 s91, 0, 0x14000
	v_add_u32_e32 v186, s91, v212
	s_add_i32 s16, s90, s38
	ds_read_b128 v[178:181], v186
	ds_read_b128 v[182:185], v186 offset:1024
	ds_read_b128 v[200:203], v186 offset:2048
	ds_read_b128 v[204:207], v186 offset:3072
	v_lshl_add_u64 v[186:187], s[86:87], 0, v[0:1]
	s_mov_b32 m0, s16
	v_lshl_add_u64 v[208:209], s[86:87], 0, v[194:195]
	global_load_lds_dwordx4 v[186:187], off
	s_add_i32 m0, s16, 0x2000
	s_nop 0
	global_load_lds_dwordx4 v[208:209], off
	s_barrier
	s_waitcnt lgkmcnt(0)
	s_waitcnt lgkmcnt(0)
	v_mfma_f32_16x16x32_bf16 v[118:121], v[178:181], v[146:149], v[118:121]
	v_mfma_f32_16x16x32_bf16 v[114:117], v[200:203], v[146:149], v[114:117]
	v_mfma_f32_16x16x32_bf16 v[102:105], v[178:181], v[154:157], v[102:105]
	v_mfma_f32_16x16x32_bf16 v[98:101], v[200:203], v[154:157], v[98:101]
	v_mfma_f32_16x16x32_bf16 v[86:89], v[178:181], v[162:165], v[86:89]
	v_mfma_f32_16x16x32_bf16 v[82:85], v[200:203], v[162:165], v[82:85]
	v_mfma_f32_16x16x32_bf16 v[70:73], v[178:181], v[170:173], v[70:73]
	v_mfma_f32_16x16x32_bf16 v[66:69], v[200:203], v[170:173], v[66:69]
	v_mfma_f32_16x16x32_bf16 v[118:121], v[182:185], v[150:153], v[118:121]
	v_mfma_f32_16x16x32_bf16 v[114:117], v[204:207], v[150:153], v[114:117]
	v_mfma_f32_16x16x32_bf16 v[102:105], v[182:185], v[158:161], v[102:105]
	v_mfma_f32_16x16x32_bf16 v[98:101], v[204:207], v[158:161], v[98:101]
	v_mfma_f32_16x16x32_bf16 v[86:89], v[182:185], v[166:169], v[86:89]
	v_mfma_f32_16x16x32_bf16 v[82:85], v[204:207], v[166:169], v[82:85]
	v_mfma_f32_16x16x32_bf16 v[70:73], v[182:185], v[174:177], v[70:73]
	v_mfma_f32_16x16x32_bf16 v[66:69], v[204:207], v[174:177], v[66:69]
	s_mov_b32 m0, s39
	v_lshl_add_u64 v[210:211], s[88:89], 0, v[190:191]
	s_barrier
	ds_read_b128 v[146:149], v213 offset:16384
	ds_read_b128 v[150:153], v213 offset:17408
	ds_read_b128 v[154:157], v213 offset:18432
	ds_read_b128 v[158:161], v213 offset:19456
	ds_read_b128 v[162:165], v213 offset:20480
	ds_read_b128 v[166:169], v213 offset:21504
	ds_read_b128 v[170:173], v213 offset:22528
	ds_read_b128 v[174:177], v213 offset:23552
	global_load_lds_dwordx4 v[210:211], off
	v_lshl_add_u64 v[214:215], s[88:89], 0, v[192:193]
	s_mov_b32 m0, s42
	s_nop 0
	global_load_lds_dwordx4 v[214:215], off
	s_barrier
	s_waitcnt lgkmcnt(0)
	s_waitcnt lgkmcnt(0)
	v_mfma_f32_16x16x32_bf16 v[62:65], v[130:133], v[146:149], v[62:65]
	v_mfma_f32_16x16x32_bf16 v[58:61], v[138:141], v[146:149], v[58:61]
	v_mfma_f32_16x16x32_bf16 v[46:49], v[130:133], v[154:157], v[46:49]
	v_mfma_f32_16x16x32_bf16 v[42:45], v[138:141], v[154:157], v[42:45]
	v_mfma_f32_16x16x32_bf16 v[30:33], v[130:133], v[162:165], v[30:33]
	v_mfma_f32_16x16x32_bf16 v[26:29], v[138:141], v[162:165], v[26:29]
	v_mfma_f32_16x16x32_bf16 v[14:17], v[130:133], v[170:173], v[14:17]
	v_mfma_f32_16x16x32_bf16 v[10:13], v[138:141], v[170:173], v[10:13]
	v_mfma_f32_16x16x32_bf16 v[62:65], v[134:137], v[150:153], v[62:65]
	v_mfma_f32_16x16x32_bf16 v[58:61], v[142:145], v[150:153], v[58:61]
	v_mfma_f32_16x16x32_bf16 v[46:49], v[134:137], v[158:161], v[46:49]
	v_mfma_f32_16x16x32_bf16 v[42:45], v[142:145], v[158:161], v[42:45]
	v_mfma_f32_16x16x32_bf16 v[30:33], v[134:137], v[166:169], v[30:33]
	v_mfma_f32_16x16x32_bf16 v[26:29], v[142:145], v[166:169], v[26:29]
	v_mfma_f32_16x16x32_bf16 v[14:17], v[134:137], v[174:177], v[14:17]
	v_mfma_f32_16x16x32_bf16 v[10:13], v[142:145], v[174:177], v[10:13]
	s_barrier
	s_add_u32 s16, s86, 0xb0000
	s_addc_u32 s17, s87, 0
	s_add_i32 s90, s91, s38
	v_lshl_add_u64 v[130:131], s[16:17], 0, v[0:1]
	s_mov_b32 m0, s90
	s_nop 0
	global_load_lds_dwordx4 v[130:131], off
	v_lshl_add_u64 v[130:131], s[16:17], 0, v[194:195]
	s_add_i32 m0, s90, 0x2000
	s_nop 0
	global_load_lds_dwordx4 v[130:131], off
	s_waitcnt vmcnt(6)
	s_barrier
	v_mfma_f32_16x16x32_bf16 v[54:57], v[178:181], v[146:149], v[54:57]
	v_mfma_f32_16x16x32_bf16 v[50:53], v[200:203], v[146:149], v[50:53]
	v_mfma_f32_16x16x32_bf16 v[38:41], v[178:181], v[154:157], v[38:41]
	v_mfma_f32_16x16x32_bf16 v[34:37], v[200:203], v[154:157], v[34:37]
	v_mfma_f32_16x16x32_bf16 v[22:25], v[178:181], v[162:165], v[22:25]
	v_mfma_f32_16x16x32_bf16 v[18:21], v[200:203], v[162:165], v[18:21]
	v_mfma_f32_16x16x32_bf16 v[6:9], v[178:181], v[170:173], v[6:9]
	v_mfma_f32_16x16x32_bf16 v[2:5], v[200:203], v[170:173], v[2:5]
	v_mfma_f32_16x16x32_bf16 v[54:57], v[182:185], v[150:153], v[54:57]
	v_mfma_f32_16x16x32_bf16 v[50:53], v[204:207], v[150:153], v[50:53]
	v_mfma_f32_16x16x32_bf16 v[38:41], v[182:185], v[158:161], v[38:41]
	v_mfma_f32_16x16x32_bf16 v[34:37], v[204:207], v[158:161], v[34:37]
	v_mfma_f32_16x16x32_bf16 v[22:25], v[182:185], v[166:169], v[22:25]
	v_mfma_f32_16x16x32_bf16 v[18:21], v[204:207], v[166:169], v[18:21]
	v_mfma_f32_16x16x32_bf16 v[6:9], v[182:185], v[174:177], v[6:9]
	v_mfma_f32_16x16x32_bf16 v[2:5], v[204:207], v[174:177], v[2:5]
	s_add_i32 s90, 0, 0x18000
	v_add_u32_e32 v142, s90, v212
	s_barrier
	ds_read_b128 v[130:133], v142
	ds_read_b128 v[134:137], v142 offset:1024
	ds_read_b128 v[138:141], v142 offset:2048
	ds_read_b128 v[142:145], v142 offset:3072
	s_add_u32 s16, s88, 0xb0000
	s_addc_u32 s17, s89, 0
	s_mov_b32 m0, s43
	v_lshl_add_u64 v[178:179], s[16:17], 0, v[190:191]
	ds_read_b128 v[146:149], v213 offset:32768
	ds_read_b128 v[150:153], v213 offset:33792
	ds_read_b128 v[154:157], v213 offset:34816
	ds_read_b128 v[158:161], v213 offset:35840
	ds_read_b128 v[162:165], v213 offset:36864
	ds_read_b128 v[166:169], v213 offset:37888
	ds_read_b128 v[170:173], v213 offset:38912
	ds_read_b128 v[174:177], v213 offset:39936
	global_load_lds_dwordx4 v[178:179], off
	v_lshl_add_u64 v[178:179], s[16:17], 0, v[192:193]
	s_mov_b32 m0, s44
	s_nop 0
	global_load_lds_dwordx4 v[178:179], off
	s_waitcnt lgkmcnt(8)
	s_barrier
	s_waitcnt lgkmcnt(0)
	s_waitcnt lgkmcnt(0)
	v_mfma_f32_16x16x32_bf16 v[126:129], v[130:133], v[146:149], v[126:129]
	v_mfma_f32_16x16x32_bf16 v[122:125], v[138:141], v[146:149], v[122:125]
	v_mfma_f32_16x16x32_bf16 v[110:113], v[130:133], v[154:157], v[110:113]
	v_mfma_f32_16x16x32_bf16 v[106:109], v[138:141], v[154:157], v[106:109]
	v_mfma_f32_16x16x32_bf16 v[94:97], v[130:133], v[162:165], v[94:97]
	v_mfma_f32_16x16x32_bf16 v[90:93], v[138:141], v[162:165], v[90:93]
	v_mfma_f32_16x16x32_bf16 v[78:81], v[130:133], v[170:173], v[78:81]
	v_mfma_f32_16x16x32_bf16 v[74:77], v[138:141], v[170:173], v[74:77]
	v_mfma_f32_16x16x32_bf16 v[126:129], v[134:137], v[150:153], v[126:129]
	v_mfma_f32_16x16x32_bf16 v[122:125], v[142:145], v[150:153], v[122:125]
	v_mfma_f32_16x16x32_bf16 v[110:113], v[134:137], v[158:161], v[110:113]
	v_mfma_f32_16x16x32_bf16 v[106:109], v[142:145], v[158:161], v[106:109]
	v_mfma_f32_16x16x32_bf16 v[94:97], v[134:137], v[166:169], v[94:97]
	v_mfma_f32_16x16x32_bf16 v[90:93], v[142:145], v[166:169], v[90:93]
	v_mfma_f32_16x16x32_bf16 v[78:81], v[134:137], v[174:177], v[78:81]
	v_mfma_f32_16x16x32_bf16 v[74:77], v[142:145], v[174:177], v[74:77]
	s_barrier
	s_add_i32 s88, 0, 0x1c000
	s_add_i32 s16, s90, s38
	v_add_u32_e32 v204, s88, v212
	v_lshl_add_u64 v[186:187], v[186:187], 0, s[40:41]
	s_mov_b32 m0, s16
	ds_read_b128 v[178:181], v204
	ds_read_b128 v[182:185], v204 offset:1024
	ds_read_b128 v[200:203], v204 offset:2048
	ds_read_b128 v[204:207], v204 offset:3072
	global_load_lds_dwordx4 v[186:187], off
	v_lshl_add_u64 v[186:187], v[208:209], 0, s[40:41]
	s_add_i32 m0, s16, 0x2000
	s_nop 0
	global_load_lds_dwordx4 v[186:187], off
	s_barrier
	s_waitcnt lgkmcnt(0)
	s_waitcnt lgkmcnt(0)
	v_mfma_f32_16x16x32_bf16 v[118:121], v[178:181], v[146:149], v[118:121]
	v_mfma_f32_16x16x32_bf16 v[114:117], v[200:203], v[146:149], v[114:117]
	v_mfma_f32_16x16x32_bf16 v[102:105], v[178:181], v[154:157], v[102:105]
	v_mfma_f32_16x16x32_bf16 v[98:101], v[200:203], v[154:157], v[98:101]
	v_mfma_f32_16x16x32_bf16 v[86:89], v[178:181], v[162:165], v[86:89]
	v_mfma_f32_16x16x32_bf16 v[82:85], v[200:203], v[162:165], v[82:85]
	v_mfma_f32_16x16x32_bf16 v[70:73], v[178:181], v[170:173], v[70:73]
	v_mfma_f32_16x16x32_bf16 v[66:69], v[200:203], v[170:173], v[66:69]
	v_mfma_f32_16x16x32_bf16 v[118:121], v[182:185], v[150:153], v[118:121]
	v_mfma_f32_16x16x32_bf16 v[114:117], v[204:207], v[150:153], v[114:117]
	v_mfma_f32_16x16x32_bf16 v[102:105], v[182:185], v[158:161], v[102:105]
	v_mfma_f32_16x16x32_bf16 v[98:101], v[204:207], v[158:161], v[98:101]
	v_mfma_f32_16x16x32_bf16 v[86:89], v[182:185], v[166:169], v[86:89]
	v_mfma_f32_16x16x32_bf16 v[82:85], v[204:207], v[166:169], v[82:85]
	v_mfma_f32_16x16x32_bf16 v[70:73], v[182:185], v[174:177], v[70:73]
	v_mfma_f32_16x16x32_bf16 v[66:69], v[204:207], v[174:177], v[66:69]
	s_mov_b32 m0, s60
	v_lshl_add_u64 v[186:187], v[210:211], 0, s[40:41]
	s_barrier
	ds_read_b128 v[146:149], v213 offset:49152
	ds_read_b128 v[150:153], v213 offset:50176
	ds_read_b128 v[154:157], v213 offset:51200
	ds_read_b128 v[158:161], v213 offset:52224
	ds_read_b128 v[162:165], v213 offset:53248
	ds_read_b128 v[166:169], v213 offset:54272
	ds_read_b128 v[170:173], v213 offset:55296
	ds_read_b128 v[174:177], v213 offset:56320
	global_load_lds_dwordx4 v[186:187], off
	v_lshl_add_u64 v[186:187], v[214:215], 0, s[40:41]
	s_mov_b32 m0, s61
	s_nop 0
	global_load_lds_dwordx4 v[186:187], off
	s_barrier
	s_waitcnt lgkmcnt(0)
	s_waitcnt lgkmcnt(0)
	v_mfma_f32_16x16x32_bf16 v[62:65], v[130:133], v[146:149], v[62:65]
	v_mfma_f32_16x16x32_bf16 v[58:61], v[138:141], v[146:149], v[58:61]
	v_mfma_f32_16x16x32_bf16 v[46:49], v[130:133], v[154:157], v[46:49]
	v_mfma_f32_16x16x32_bf16 v[42:45], v[138:141], v[154:157], v[42:45]
	v_mfma_f32_16x16x32_bf16 v[30:33], v[130:133], v[162:165], v[30:33]
	v_mfma_f32_16x16x32_bf16 v[26:29], v[138:141], v[162:165], v[26:29]
	v_mfma_f32_16x16x32_bf16 v[14:17], v[130:133], v[170:173], v[14:17]
	v_mfma_f32_16x16x32_bf16 v[10:13], v[138:141], v[170:173], v[10:13]
	v_mfma_f32_16x16x32_bf16 v[62:65], v[134:137], v[150:153], v[62:65]
	v_mfma_f32_16x16x32_bf16 v[58:61], v[142:145], v[150:153], v[58:61]
	v_mfma_f32_16x16x32_bf16 v[46:49], v[134:137], v[158:161], v[46:49]
	v_mfma_f32_16x16x32_bf16 v[42:45], v[142:145], v[158:161], v[42:45]
	v_mfma_f32_16x16x32_bf16 v[30:33], v[134:137], v[166:169], v[30:33]
	v_mfma_f32_16x16x32_bf16 v[26:29], v[142:145], v[166:169], v[26:29]
	v_mfma_f32_16x16x32_bf16 v[14:17], v[134:137], v[174:177], v[14:17]
	v_mfma_f32_16x16x32_bf16 v[10:13], v[142:145], v[174:177], v[10:13]
	s_barrier
	s_add_u32 s16, s86, 0xb0080
	s_addc_u32 s17, s87, 0
	s_add_i32 s86, s88, s38
	v_lshl_add_u64 v[130:131], s[16:17], 0, v[0:1]
	s_mov_b32 m0, s86
	s_nop 0
	global_load_lds_dwordx4 v[130:131], off
	v_lshl_add_u64 v[130:131], s[16:17], 0, v[194:195]
	s_add_i32 m0, s86, 0x2000
	s_nop 0
	global_load_lds_dwordx4 v[130:131], off
	s_waitcnt vmcnt(6)
	s_barrier
	v_mfma_f32_16x16x32_bf16 v[54:57], v[178:181], v[146:149], v[54:57]
	v_mfma_f32_16x16x32_bf16 v[50:53], v[200:203], v[146:149], v[50:53]
	v_mfma_f32_16x16x32_bf16 v[38:41], v[178:181], v[154:157], v[38:41]
	v_mfma_f32_16x16x32_bf16 v[34:37], v[200:203], v[154:157], v[34:37]
	v_mfma_f32_16x16x32_bf16 v[22:25], v[178:181], v[162:165], v[22:25]
	v_mfma_f32_16x16x32_bf16 v[18:21], v[200:203], v[162:165], v[18:21]
	v_mfma_f32_16x16x32_bf16 v[6:9], v[178:181], v[170:173], v[6:9]
	v_mfma_f32_16x16x32_bf16 v[2:5], v[200:203], v[170:173], v[2:5]
	v_mfma_f32_16x16x32_bf16 v[54:57], v[182:185], v[150:153], v[54:57]
	v_mfma_f32_16x16x32_bf16 v[50:53], v[204:207], v[150:153], v[50:53]
	v_mfma_f32_16x16x32_bf16 v[38:41], v[182:185], v[158:161], v[38:41]
	v_mfma_f32_16x16x32_bf16 v[34:37], v[204:207], v[158:161], v[34:37]
	v_mfma_f32_16x16x32_bf16 v[22:25], v[182:185], v[166:169], v[22:25]
	v_mfma_f32_16x16x32_bf16 v[18:21], v[204:207], v[166:169], v[18:21]
	v_mfma_f32_16x16x32_bf16 v[6:9], v[182:185], v[174:177], v[6:9]
	v_mfma_f32_16x16x32_bf16 v[2:5], v[204:207], v[174:177], v[2:5]
	s_add_i32 s79, s79, 2
	s_add_u32 s34, s34, 0x100
	s_addc_u32 s78, s78, 0
	s_cmp_gt_u32 s79, 41
	s_mov_b64 s[16:17], s[84:85]
	s_barrier
	s_cbranch_scc0 .LBB0_1090
	s_lshl_b32 s16, s23, 8
	v_mov_b32_e32 v186, v252
	s_add_i32 s16, s16, s47
	s_nop 0
	v_and_or_b32 v202, v186, 15, s16
	s_lshl_b32 s16, s22, 8
	s_or_b32 s16, s16, s55
	v_lshrrev_b32_e32 v130, 1, v186
	v_and_or_b32 v200, v130, 24, s16
	v_ashrrev_i32_e32 v201, 31, v200
	v_ashrrev_i32_e32 v203, 31, v202
	v_lshl_add_u64 v[204:205], v[200:201], 2, s[12:13]
	v_lshlrev_b64 v[130:131], 12, v[202:203]
	v_lshl_add_u64 v[130:131], v[204:205], 0, v[130:131]
	global_load_dwordx4 v[216:219], v[130:131], off offset:16
	global_load_dwordx4 v[220:223], v[130:131], off
	global_load_dwordx4 v[178:181], v[130:131], off offset:528
	global_load_dwordx4 v[182:185], v[130:131], off offset:512
	v_or_b32_e32 v210, 16, v202
	v_ashrrev_i32_e32 v211, 31, v210
	v_lshlrev_b64 v[130:131], 12, v[210:211]
	v_or_b32_e32 v208, 32, v202
	v_lshl_add_u64 v[130:131], v[204:205], 0, v[130:131]
	v_ashrrev_i32_e32 v209, 31, v208
	global_load_dwordx4 v[170:173], v[130:131], off offset:16
	global_load_dwordx4 v[174:177], v[130:131], off
	global_load_dwordx4 v[162:165], v[130:131], off offset:528
	global_load_dwordx4 v[166:169], v[130:131], off offset:512
	v_lshlrev_b64 v[130:131], 12, v[208:209]
	v_or_b32_e32 v206, 48, v202
	v_lshl_add_u64 v[130:131], v[204:205], 0, v[130:131]
	v_ashrrev_i32_e32 v207, 31, v206
	global_load_dwordx4 v[154:157], v[130:131], off offset:16
	global_load_dwordx4 v[158:161], v[130:131], off
	global_load_dwordx4 v[138:141], v[130:131], off offset:528
	global_load_dwordx4 v[142:145], v[130:131], off offset:512
	v_lshlrev_b64 v[130:131], 12, v[206:207]
	v_lshl_add_u64 v[134:135], v[204:205], 0, v[130:131]
	global_load_dwordx4 v[146:149], v[134:135], off offset:16
	global_load_dwordx4 v[150:153], v[134:135], off
	global_load_dwordx4 v[130:133], v[134:135], off offset:528
	s_nop 0
	global_load_dwordx4 v[134:137], v[134:135], off offset:512
	v_and_b32_e32 v186, 63, v186
	v_lshlrev_b32_e32 v187, 2, v186
	v_xor_b32_e32 v215, 64, v187
	v_xor_b32_e32 v214, 0x80, v187
	v_cmp_gt_u32_e32 vcc, 16, v186
	v_lshlrev_b64 v[186:187], 10, v[202:203]
	v_lshl_add_u64 v[186:187], v[186:187], 0, v[200:201]
	s_lshl_b32 s16, s22, 2
	s_ashr_i32 s17, s16, 31
	s_waitcnt vmcnt(0)
	v_pk_add_f32 v[124:125], v[124:125], v[218:219]
	v_pk_add_f32 v[128:129], v[128:129], v[222:223]
	v_pk_add_f32 v[126:127], v[126:127], v[220:221]
	v_pk_mul_f32 v[218:219], v[128:129], v[128:129]
	v_pk_mul_f32 v[220:221], v[126:127], v[126:127]
	v_pk_add_f32 v[122:123], v[122:123], v[216:217]
	v_lshl_add_u64 v[216:217], v[186:187], 2, s[14:15]
	v_add_f32_e32 v220, v220, v221
	v_add_f32_e32 v218, v218, v219
	global_store_dwordx4 v[216:217], v[126:129], off
	global_store_dwordx4 v[216:217], v[122:125], off offset:16
	v_add_f32_e32 v222, v220, v218
	v_pk_mul_f32 v[220:221], v[122:123], v[122:123]
	v_cvt_pk_bf16_f32 v126, v126, v127
	v_cvt_pk_bf16_f32 v127, v128, v129
	v_cvt_pk_bf16_f32 v128, v122, v123
	v_cvt_pk_bf16_f32 v129, v124, v125
	v_lshl_add_u64 v[122:123], v[186:187], 1, s[80:81]
	v_pk_add_f32 v[120:121], v[120:121], v[184:185]
	v_pk_add_f32 v[118:119], v[118:119], v[182:183]
	v_pk_mul_f32 v[218:219], v[124:125], v[124:125]
	global_store_dwordx4 v[122:123], v[126:129], off
	v_pk_mul_f32 v[124:125], v[120:121], v[120:121]
	v_pk_add_f32 v[116:117], v[116:117], v[180:181]
	v_pk_mul_f32 v[126:127], v[118:119], v[118:119]
	v_pk_add_f32 v[114:115], v[114:115], v[178:179]
	v_add_f32_e32 v126, v126, v127
	v_add_f32_e32 v124, v124, v125
	v_add_f32_e32 v128, v126, v124
	v_pk_mul_f32 v[124:125], v[116:117], v[116:117]
	v_pk_mul_f32 v[126:127], v[114:115], v[114:115]
	v_add_f32_e32 v220, v220, v221
	v_add_f32_e32 v218, v218, v219
	v_add_f32_e32 v126, v126, v127
	v_add_f32_e32 v124, v124, v125
	v_add_f32_e32 v218, v220, v218
	v_add_f32_e32 v124, v126, v124
	v_add_f32_e32 v218, v222, v218
	v_add_f32_e32 v124, v128, v124
	v_add_f32_e32 v124, v218, v124
	global_store_dwordx4 v[216:217], v[118:121], off offset:512
	global_store_dwordx4 v[216:217], v[114:117], off offset:528
	s_nop 0
	v_cvt_pk_bf16_f32 v118, v118, v119
	v_cvt_pk_bf16_f32 v119, v120, v121
	v_cvt_pk_bf16_f32 v120, v114, v115
	ds_bpermute_b32 v114, v215, v124
	v_cvt_pk_bf16_f32 v121, v116, v117
	global_store_dwordx4 v[122:123], v[118:121], off offset:256
	s_waitcnt lgkmcnt(0)
	v_add_f32_e32 v114, v124, v114
	ds_bpermute_b32 v115, v214, v114
	s_and_saveexec_b64 s[22:23], vcc
	s_cbranch_execz .LBB0_1093
	v_lshlrev_b64 v[116:117], 6, v[202:203]
	v_lshl_add_u64 v[116:117], s[82:83], 0, v[116:117]
	v_lshl_add_u64 v[116:117], s[16:17], 2, v[116:117]
	s_lshl_b32 s34, s45, 2
	v_lshl_add_u64 v[116:117], v[116:117], 0, s[34:35]
	s_waitcnt lgkmcnt(0)
	v_add_f32_e32 v114, v114, v115
	global_store_dword v[116:117], v114, off

.LBB0_1209:
	s_add_u32 s87, s88, 0xfffc0080
	s_addc_u32 s90, s89, -1
	s_add_i32 s94, 0, 0x10000
	s_waitcnt lgkmcnt(0)
	v_add_u32_e32 v0, s94, v170
	ds_read_b128 v[130:133], v0
	ds_read_b128 v[134:137], v0 offset:1024
	ds_read_b128 v[138:141], v0 offset:2048
	ds_read_b128 v[142:145], v0 offset:3072
	s_cmp_eq_u32 s85, 12
	s_cselect_b32 s93, s13, s90
	s_cselect_b32 s92, s22, s87
	s_cselect_b32 s91, s7, s79
	s_cselect_b32 s90, s23, s34
	v_lshl_add_u64 v[194:195], s[88:89], 0, v[154:155]
	s_add_i32 m0, s39, 0xc000
	ds_read_b128 v[158:161], v171
	ds_read_b128 v[162:165], v171 offset:1024
	ds_read_b128 v[166:169], v171 offset:2048
	ds_read_b128 v[172:175], v171 offset:3072
	ds_read_b128 v[176:179], v171 offset:4096
	ds_read_b128 v[180:183], v171 offset:5120
	ds_read_b128 v[184:187], v171 offset:6144
	ds_read_b128 v[190:193], v171 offset:7168
	global_load_lds_dwordx4 v[194:195], off
	v_lshl_add_u64 v[194:195], s[88:89], 0, v[156:157]
	s_add_i32 m0, s39, 0xe000
	s_nop 0
	global_load_lds_dwordx4 v[194:195], off
	s_waitcnt lgkmcnt(8)
	s_barrier
	s_waitcnt lgkmcnt(0)
	s_waitcnt lgkmcnt(0)
	v_mfma_f32_16x16x32_bf16 v[126:129], v[130:133], v[158:161], v[126:129]
	v_mfma_f32_16x16x32_bf16 v[122:125], v[138:141], v[158:161], v[122:125]
	v_mfma_f32_16x16x32_bf16 v[110:113], v[130:133], v[166:169], v[110:113]
	v_mfma_f32_16x16x32_bf16 v[106:109], v[138:141], v[166:169], v[106:109]
	v_mfma_f32_16x16x32_bf16 v[94:97], v[130:133], v[176:179], v[94:97]
	v_mfma_f32_16x16x32_bf16 v[90:93], v[138:141], v[176:179], v[90:93]
	v_mfma_f32_16x16x32_bf16 v[78:81], v[130:133], v[184:187], v[78:81]
	v_mfma_f32_16x16x32_bf16 v[74:77], v[138:141], v[184:187], v[74:77]
	v_mfma_f32_16x16x32_bf16 v[126:129], v[134:137], v[162:165], v[126:129]
	v_mfma_f32_16x16x32_bf16 v[122:125], v[142:145], v[162:165], v[122:125]
	v_mfma_f32_16x16x32_bf16 v[110:113], v[134:137], v[172:175], v[110:113]
	v_mfma_f32_16x16x32_bf16 v[106:109], v[142:145], v[172:175], v[106:109]
	v_mfma_f32_16x16x32_bf16 v[94:97], v[134:137], v[180:183], v[94:97]
	v_mfma_f32_16x16x32_bf16 v[90:93], v[142:145], v[180:183], v[90:93]
	v_mfma_f32_16x16x32_bf16 v[78:81], v[134:137], v[190:193], v[78:81]
	v_mfma_f32_16x16x32_bf16 v[74:77], v[142:145], v[190:193], v[74:77]
	s_barrier
	s_add_i32 s87, 0, 0x14000
	s_add_i32 s94, s94, s38
	v_add_u32_e32 v0, s87, v170
	v_lshl_add_u64 v[210:211], s[90:91], 0, v[148:149]
	s_mov_b32 m0, s94
	ds_read_b128 v[194:197], v0
	ds_read_b128 v[198:201], v0 offset:1024
	ds_read_b128 v[202:205], v0 offset:2048
	ds_read_b128 v[206:209], v0 offset:3072
	global_load_lds_dwordx4 v[210:211], off
	v_lshl_add_u64 v[212:213], s[90:91], 0, v[152:153]
	s_add_i32 m0, s94, 0x2000
	s_nop 0
	global_load_lds_dwordx4 v[212:213], off
	s_barrier
	s_waitcnt lgkmcnt(0)
	s_waitcnt lgkmcnt(0)
	v_mfma_f32_16x16x32_bf16 v[118:121], v[194:197], v[158:161], v[118:121]
	v_mfma_f32_16x16x32_bf16 v[114:117], v[202:205], v[158:161], v[114:117]
	v_mfma_f32_16x16x32_bf16 v[102:105], v[194:197], v[166:169], v[102:105]
	v_mfma_f32_16x16x32_bf16 v[98:101], v[202:205], v[166:169], v[98:101]
	v_mfma_f32_16x16x32_bf16 v[86:89], v[194:197], v[176:179], v[86:89]
	v_mfma_f32_16x16x32_bf16 v[82:85], v[202:205], v[176:179], v[82:85]
	v_mfma_f32_16x16x32_bf16 v[70:73], v[194:197], v[184:187], v[70:73]
	v_mfma_f32_16x16x32_bf16 v[66:69], v[202:205], v[184:187], v[66:69]
	v_mfma_f32_16x16x32_bf16 v[118:121], v[198:201], v[162:165], v[118:121]
	v_mfma_f32_16x16x32_bf16 v[114:117], v[206:209], v[162:165], v[114:117]
	v_mfma_f32_16x16x32_bf16 v[102:105], v[198:201], v[172:175], v[102:105]
	v_mfma_f32_16x16x32_bf16 v[98:101], v[206:209], v[172:175], v[98:101]
	v_mfma_f32_16x16x32_bf16 v[86:89], v[198:201], v[180:183], v[86:89]
	v_mfma_f32_16x16x32_bf16 v[82:85], v[206:209], v[180:183], v[82:85]
	v_mfma_f32_16x16x32_bf16 v[70:73], v[198:201], v[190:193], v[70:73]
	v_mfma_f32_16x16x32_bf16 v[66:69], v[206:209], v[190:193], v[66:69]
	s_mov_b32 m0, s39
	v_lshl_add_u64 v[214:215], s[92:93], 0, v[146:147]
	s_barrier
	ds_read_b128 v[158:161], v171 offset:16384
	ds_read_b128 v[162:165], v171 offset:17408
	ds_read_b128 v[166:169], v171 offset:18432
	ds_read_b128 v[172:175], v171 offset:19456
	ds_read_b128 v[176:179], v171 offset:20480
	ds_read_b128 v[180:183], v171 offset:21504
	ds_read_b128 v[184:187], v171 offset:22528
	ds_read_b128 v[190:193], v171 offset:23552
	global_load_lds_dwordx4 v[214:215], off
	v_lshl_add_u64 v[216:217], s[92:93], 0, v[150:151]
	s_mov_b32 m0, s42
	s_nop 0
	global_load_lds_dwordx4 v[216:217], off
	s_barrier
	s_waitcnt lgkmcnt(0)
	s_waitcnt lgkmcnt(0)
	v_mfma_f32_16x16x32_bf16 v[62:65], v[130:133], v[158:161], v[62:65]
	v_mfma_f32_16x16x32_bf16 v[58:61], v[138:141], v[158:161], v[58:61]
	v_mfma_f32_16x16x32_bf16 v[46:49], v[130:133], v[166:169], v[46:49]
	v_mfma_f32_16x16x32_bf16 v[42:45], v[138:141], v[166:169], v[42:45]
	v_mfma_f32_16x16x32_bf16 v[30:33], v[130:133], v[176:179], v[30:33]
	v_mfma_f32_16x16x32_bf16 v[26:29], v[138:141], v[176:179], v[26:29]
	v_mfma_f32_16x16x32_bf16 v[14:17], v[130:133], v[184:187], v[14:17]
	v_mfma_f32_16x16x32_bf16 v[10:13], v[138:141], v[184:187], v[10:13]
	v_mfma_f32_16x16x32_bf16 v[62:65], v[134:137], v[162:165], v[62:65]
	v_mfma_f32_16x16x32_bf16 v[58:61], v[142:145], v[162:165], v[58:61]
	v_mfma_f32_16x16x32_bf16 v[46:49], v[134:137], v[172:175], v[46:49]
	v_mfma_f32_16x16x32_bf16 v[42:45], v[142:145], v[172:175], v[42:45]
	v_mfma_f32_16x16x32_bf16 v[30:33], v[134:137], v[180:183], v[30:33]
	v_mfma_f32_16x16x32_bf16 v[26:29], v[142:145], v[180:183], v[26:29]
	v_mfma_f32_16x16x32_bf16 v[14:17], v[134:137], v[190:193], v[14:17]
	v_mfma_f32_16x16x32_bf16 v[10:13], v[142:145], v[190:193], v[10:13]
	s_barrier
	s_add_u32 s94, s90, 0x40000
	s_addc_u32 s95, s91, 0
	s_add_i32 s87, s87, s38
	v_lshl_add_u64 v[130:131], s[94:95], 0, v[148:149]
	s_mov_b32 m0, s87
	s_nop 0
	global_load_lds_dwordx4 v[130:131], off
	v_lshl_add_u64 v[130:131], s[94:95], 0, v[152:153]
	s_add_i32 m0, s87, 0x2000
	s_nop 0
	global_load_lds_dwordx4 v[130:131], off
	s_waitcnt vmcnt(6)
	s_barrier
	v_mfma_f32_16x16x32_bf16 v[54:57], v[194:197], v[158:161], v[54:57]
	v_mfma_f32_16x16x32_bf16 v[50:53], v[202:205], v[158:161], v[50:53]
	v_mfma_f32_16x16x32_bf16 v[38:41], v[194:197], v[166:169], v[38:41]
	v_mfma_f32_16x16x32_bf16 v[34:37], v[202:205], v[166:169], v[34:37]
	v_mfma_f32_16x16x32_bf16 v[22:25], v[194:197], v[176:179], v[22:25]
	v_mfma_f32_16x16x32_bf16 v[18:21], v[202:205], v[176:179], v[18:21]
	v_mfma_f32_16x16x32_bf16 v[6:9], v[194:197], v[184:187], v[6:9]
	v_mfma_f32_16x16x32_bf16 v[2:5], v[202:205], v[184:187], v[2:5]
	v_mfma_f32_16x16x32_bf16 v[54:57], v[198:201], v[162:165], v[54:57]
	v_mfma_f32_16x16x32_bf16 v[50:53], v[206:209], v[162:165], v[50:53]
	v_mfma_f32_16x16x32_bf16 v[38:41], v[198:201], v[172:175], v[38:41]
	v_mfma_f32_16x16x32_bf16 v[34:37], v[206:209], v[172:175], v[34:37]
	v_mfma_f32_16x16x32_bf16 v[22:25], v[198:201], v[180:183], v[22:25]
	v_mfma_f32_16x16x32_bf16 v[18:21], v[206:209], v[180:183], v[18:21]
	v_mfma_f32_16x16x32_bf16 v[6:9], v[198:201], v[190:193], v[6:9]
	v_mfma_f32_16x16x32_bf16 v[2:5], v[206:209], v[190:193], v[2:5]
	s_add_i32 s87, 0, 0x18000
	v_add_u32_e32 v0, s87, v170
	s_barrier
	ds_read_b128 v[130:133], v0
	ds_read_b128 v[134:137], v0 offset:1024
	ds_read_b128 v[138:141], v0 offset:2048
	ds_read_b128 v[142:145], v0 offset:3072
	s_add_u32 s92, s92, 0x40000
	s_addc_u32 s93, s93, 0
	s_mov_b32 m0, s43
	v_lshl_add_u64 v[194:195], s[92:93], 0, v[146:147]
	ds_read_b128 v[158:161], v171 offset:32768
	ds_read_b128 v[162:165], v171 offset:33792
	ds_read_b128 v[166:169], v171 offset:34816
	ds_read_b128 v[172:175], v171 offset:35840
	ds_read_b128 v[176:179], v171 offset:36864
	ds_read_b128 v[180:183], v171 offset:37888
	ds_read_b128 v[184:187], v171 offset:38912
	ds_read_b128 v[190:193], v171 offset:39936
	global_load_lds_dwordx4 v[194:195], off
	v_lshl_add_u64 v[194:195], s[92:93], 0, v[150:151]
	s_mov_b32 m0, s44
	s_nop 0
	global_load_lds_dwordx4 v[194:195], off
	s_waitcnt lgkmcnt(8)
	s_barrier
	s_waitcnt lgkmcnt(0)
	s_waitcnt lgkmcnt(0)
	v_mfma_f32_16x16x32_bf16 v[126:129], v[130:133], v[158:161], v[126:129]
	v_mfma_f32_16x16x32_bf16 v[122:125], v[138:141], v[158:161], v[122:125]
	v_mfma_f32_16x16x32_bf16 v[110:113], v[130:133], v[166:169], v[110:113]
	v_mfma_f32_16x16x32_bf16 v[106:109], v[138:141], v[166:169], v[106:109]
	v_mfma_f32_16x16x32_bf16 v[94:97], v[130:133], v[176:179], v[94:97]
	v_mfma_f32_16x16x32_bf16 v[90:93], v[138:141], v[176:179], v[90:93]
	v_mfma_f32_16x16x32_bf16 v[78:81], v[130:133], v[184:187], v[78:81]
	v_mfma_f32_16x16x32_bf16 v[74:77], v[138:141], v[184:187], v[74:77]
	v_mfma_f32_16x16x32_bf16 v[126:129], v[134:137], v[162:165], v[126:129]
	v_mfma_f32_16x16x32_bf16 v[122:125], v[142:145], v[162:165], v[122:125]
	v_mfma_f32_16x16x32_bf16 v[110:113], v[134:137], v[172:175], v[110:113]
	v_mfma_f32_16x16x32_bf16 v[106:109], v[142:145], v[172:175], v[106:109]
	v_mfma_f32_16x16x32_bf16 v[94:97], v[134:137], v[180:183], v[94:97]
	v_mfma_f32_16x16x32_bf16 v[90:93], v[142:145], v[180:183], v[90:93]
	v_mfma_f32_16x16x32_bf16 v[78:81], v[134:137], v[190:193], v[78:81]
	v_mfma_f32_16x16x32_bf16 v[74:77], v[142:145], v[190:193], v[74:77]
	s_barrier
	s_add_i32 s92, 0, 0x1c000
	s_add_i32 s87, s87, s38
	v_add_u32_e32 v0, s92, v170
	v_lshl_add_u64 v[210:211], v[210:211], 0, s[40:41]
	s_mov_b32 m0, s87
	ds_read_b128 v[194:197], v0
	ds_read_b128 v[198:201], v0 offset:1024
	ds_read_b128 v[202:205], v0 offset:2048
	ds_read_b128 v[206:209], v0 offset:3072
	global_load_lds_dwordx4 v[210:211], off
	v_lshl_add_u64 v[210:211], v[212:213], 0, s[40:41]
	s_add_i32 m0, s87, 0x2000
	s_nop 0
	global_load_lds_dwordx4 v[210:211], off
	s_barrier
	s_waitcnt lgkmcnt(0)
	s_waitcnt lgkmcnt(0)
	v_mfma_f32_16x16x32_bf16 v[118:121], v[194:197], v[158:161], v[118:121]
	v_mfma_f32_16x16x32_bf16 v[114:117], v[202:205], v[158:161], v[114:117]
	v_mfma_f32_16x16x32_bf16 v[102:105], v[194:197], v[166:169], v[102:105]
	v_mfma_f32_16x16x32_bf16 v[98:101], v[202:205], v[166:169], v[98:101]
	v_mfma_f32_16x16x32_bf16 v[86:89], v[194:197], v[176:179], v[86:89]
	v_mfma_f32_16x16x32_bf16 v[82:85], v[202:205], v[176:179], v[82:85]
	v_mfma_f32_16x16x32_bf16 v[70:73], v[194:197], v[184:187], v[70:73]
	v_mfma_f32_16x16x32_bf16 v[66:69], v[202:205], v[184:187], v[66:69]
	v_mfma_f32_16x16x32_bf16 v[118:121], v[198:201], v[162:165], v[118:121]
	v_mfma_f32_16x16x32_bf16 v[114:117], v[206:209], v[162:165], v[114:117]
	v_mfma_f32_16x16x32_bf16 v[102:105], v[198:201], v[172:175], v[102:105]
	v_mfma_f32_16x16x32_bf16 v[98:101], v[206:209], v[172:175], v[98:101]
	v_mfma_f32_16x16x32_bf16 v[86:89], v[198:201], v[180:183], v[86:89]
	v_mfma_f32_16x16x32_bf16 v[82:85], v[206:209], v[180:183], v[82:85]
	v_mfma_f32_16x16x32_bf16 v[70:73], v[198:201], v[190:193], v[70:73]
	v_mfma_f32_16x16x32_bf16 v[66:69], v[206:209], v[190:193], v[66:69]
	s_mov_b32 m0, s60
	v_lshl_add_u64 v[210:211], v[214:215], 0, s[40:41]
	s_barrier
	ds_read_b128 v[158:161], v171 offset:49152
	ds_read_b128 v[162:165], v171 offset:50176
	ds_read_b128 v[166:169], v171 offset:51200
	ds_read_b128 v[172:175], v171 offset:52224
	ds_read_b128 v[176:179], v171 offset:53248
	ds_read_b128 v[180:183], v171 offset:54272
	ds_read_b128 v[184:187], v171 offset:55296
	ds_read_b128 v[190:193], v171 offset:56320
	global_load_lds_dwordx4 v[210:211], off
	v_lshl_add_u64 v[210:211], v[216:217], 0, s[40:41]
	s_mov_b32 m0, s61
	s_nop 0
	global_load_lds_dwordx4 v[210:211], off
	s_barrier
	s_waitcnt lgkmcnt(0)
	s_waitcnt lgkmcnt(0)
	v_mfma_f32_16x16x32_bf16 v[62:65], v[130:133], v[158:161], v[62:65]
	v_mfma_f32_16x16x32_bf16 v[58:61], v[138:141], v[158:161], v[58:61]
	v_mfma_f32_16x16x32_bf16 v[46:49], v[130:133], v[166:169], v[46:49]
	v_mfma_f32_16x16x32_bf16 v[42:45], v[138:141], v[166:169], v[42:45]
	v_mfma_f32_16x16x32_bf16 v[30:33], v[130:133], v[176:179], v[30:33]
	v_mfma_f32_16x16x32_bf16 v[26:29], v[138:141], v[176:179], v[26:29]
	v_mfma_f32_16x16x32_bf16 v[14:17], v[130:133], v[184:187], v[14:17]
	v_mfma_f32_16x16x32_bf16 v[10:13], v[138:141], v[184:187], v[10:13]
	v_mfma_f32_16x16x32_bf16 v[62:65], v[134:137], v[162:165], v[62:65]
	v_mfma_f32_16x16x32_bf16 v[58:61], v[142:145], v[162:165], v[58:61]
	v_mfma_f32_16x16x32_bf16 v[46:49], v[134:137], v[172:175], v[46:49]
	v_mfma_f32_16x16x32_bf16 v[42:45], v[142:145], v[172:175], v[42:45]
	v_mfma_f32_16x16x32_bf16 v[30:33], v[134:137], v[180:183], v[30:33]
	v_mfma_f32_16x16x32_bf16 v[26:29], v[142:145], v[180:183], v[26:29]
	v_mfma_f32_16x16x32_bf16 v[14:17], v[134:137], v[190:193], v[14:17]
	v_mfma_f32_16x16x32_bf16 v[10:13], v[142:145], v[190:193], v[10:13]
	s_barrier
	s_add_u32 s90, s90, 0x40080
	s_addc_u32 s91, s91, 0
	s_add_i32 s87, s92, s38
	v_lshl_add_u64 v[130:131], s[90:91], 0, v[148:149]
	s_mov_b32 m0, s87
	s_nop 0
	global_load_lds_dwordx4 v[130:131], off
	v_lshl_add_u64 v[130:131], s[90:91], 0, v[152:153]
	s_add_i32 m0, s87, 0x2000
	s_nop 0
	global_load_lds_dwordx4 v[130:131], off
	s_waitcnt vmcnt(6)
	s_barrier
	v_mfma_f32_16x16x32_bf16 v[54:57], v[194:197], v[158:161], v[54:57]
	v_mfma_f32_16x16x32_bf16 v[50:53], v[202:205], v[158:161], v[50:53]
	v_mfma_f32_16x16x32_bf16 v[38:41], v[194:197], v[166:169], v[38:41]
	v_mfma_f32_16x16x32_bf16 v[34:37], v[202:205], v[166:169], v[34:37]
	v_mfma_f32_16x16x32_bf16 v[22:25], v[194:197], v[176:179], v[22:25]
	v_mfma_f32_16x16x32_bf16 v[18:21], v[202:205], v[176:179], v[18:21]
	v_mfma_f32_16x16x32_bf16 v[6:9], v[194:197], v[184:187], v[6:9]
	v_mfma_f32_16x16x32_bf16 v[2:5], v[202:205], v[184:187], v[2:5]
	v_mfma_f32_16x16x32_bf16 v[54:57], v[198:201], v[162:165], v[54:57]
	v_mfma_f32_16x16x32_bf16 v[50:53], v[206:209], v[162:165], v[50:53]
	v_mfma_f32_16x16x32_bf16 v[38:41], v[198:201], v[172:175], v[38:41]
	v_mfma_f32_16x16x32_bf16 v[34:37], v[206:209], v[172:175], v[34:37]
	v_mfma_f32_16x16x32_bf16 v[22:25], v[198:201], v[180:183], v[22:25]
	v_mfma_f32_16x16x32_bf16 v[18:21], v[206:209], v[180:183], v[18:21]
	v_mfma_f32_16x16x32_bf16 v[6:9], v[198:201], v[190:193], v[6:9]
	v_mfma_f32_16x16x32_bf16 v[2:5], v[206:209], v[190:193], v[2:5]
	s_add_i32 s85, s85, 2
	s_add_u32 s88, s88, 0x100
	s_addc_u32 s89, s89, 0
	s_add_u32 s34, s34, 0x100
	s_addc_u32 s79, s79, 0
	s_cmp_gt_u32 s85, 13
	s_barrier
	s_cbranch_scc0 .LBB0_1209
	v_mov_b32_e32 v131, v252
	s_lshl_b32 s7, s86, 8
	v_and_b32_e32 v130, 63, v131
	v_or_b32_e32 v0, s72, v130
	v_lshrrev_b32_e32 v0, 1, v0
	v_and_or_b32 v132, v0, 63, s73
	v_add_u32_e32 v134, s7, v132
	v_ashrrev_i32_e32 v135, 31, v134
	v_and_b32_e32 v142, 1, v131
	v_lshlrev_b64 v[134:135], 6, v[134:135]
	v_lshl_add_u64 v[134:135], s[82:83], 0, v[134:135]
	v_lshlrev_b32_e32 v0, 5, v142
	v_lshl_add_u64 v[138:139], v[134:135], 0, v[0:1]
	global_load_dwordx4 v[134:137], v[138:139], off
	s_nop 0
	global_load_dwordx4 v[138:141], v[138:139], off offset:16
	v_lshlrev_b32_e32 v0, 2, v130
	v_cmp_eq_u32_e32 vcc, 0, v142
	s_waitcnt vmcnt(0)
	v_add_f32_e32 v133, v134, v135
	v_add_f32_e32 v134, v136, v137
	v_add_f32_e32 v135, v138, v139
	v_add_f32_e32 v136, v140, v141
	v_add_f32_e32 v133, v133, v134
	v_add_f32_e32 v134, v135, v136
	v_add_f32_e32 v133, v133, v134
	v_xor_b32_e32 v134, 4, v0
	ds_bpermute_b32 v134, v134, v133
	s_and_saveexec_b64 s[22:23], vcc
	s_cbranch_execz .LBB0_1212
	s_waitcnt lgkmcnt(0)
	v_add_f32_e32 v133, v133, v134
	v_fmamk_f32 v133, v133, 0x3a800000, v224
	s_mov_b32 s13, 0x800000
	v_mul_f32_e32 v134, 0x4b800000, v133
	v_cmp_gt_f32_e32 vcc, s13, v133
	v_lshl_add_u32 v132, v132, 2, 0
	v_add_u32_e32 v132, 0x20000, v132
	v_cndmask_b32_e32 v133, v133, v134, vcc
	v_rsq_f32_e32 v133, v133
	s_nop 0
	v_mul_f32_e32 v134, 0x45800000, v133
	v_cndmask_b32_e32 v133, v133, v134, vcc
	ds_write_b32 v132, v133
